# GEMM K-loops P1,P2,P3,P5,P6: first iteration peeled with srcC=0, accumulator zeroing (128 v_mov per wave per tile) removed
# speedup vs baseline: 1.0182x; 1.0089x over previous
; #define PG8_STAGE(bufoff, gbase, voff) do { _Pragma("unroll") for (int _i = 0; _i < 2; ++_i) \
;         __builtin_amdgcn_global_load_lds((const unsigned*)((const char*)(gbase) + (voff)[_i]), (PG8_LAS unsigned*)(lds + (bufoff) + ldsw + _i * 8192), 16, 0, 0); } while (0)
; #define PG8_LDA(dst, b, h) do { _Pragma("unroll") for (int m = 0; m < 4; ++m) _Pragma("unroll") for (int k = 0; k < 2; ++k) dst[m][k] = *(const PG8_LAS bf16x8*)(lds + PG8_SA(b, h) + aoff + m * 2048 + k * 1024); } while (0)
; #define PG8_LDB(dst, b, h) do { _Pragma("unroll") for (int n = 0; n < 2; ++n) _Pragma("unroll") for (int k = 0; k < 2; ++k) dst[n][k] = *(const PG8_LAS bf16x8*)(lds + PG8_SB(b, h) + boff + n * 2048 + k * 1024); } while (0)
; #define PG8_MMA(ai, bj, At, Bt) do { __builtin_amdgcn_s_setprio(1); _Pragma("unroll") for (int m = 0; m < 4; ++m) _Pragma("unroll") for (int n = 0; n < 2; ++n) _Pragma("unroll") for (int k = 0; k < 2; ++k) \
;         acc[ai][bj][m][n] = __builtin_amdgcn_mfma_f32_16x16x32_bf16(Bt[n][k], At[m][k], acc[ai][bj][m][n], 0, 0, 0); __builtin_amdgcn_s_setprio(0); } while (0)
; template <class Epi, class Sched, bool ALIGN_EPI = false, bool SP2 = false, bool ATILED = false>
; __device__ __forceinline__ void gemm_phase(PG8_LAS unsigned char* lds, const Gemm g, const Sched& S, const Epi& E) {
;     ...
;         const bool has_next = S.next(ui + 1, nxt);
;         const char* nA = has_next ? (const char*)g.A + (size_t)nxt.pm * tstepA : cA; const char* nB = has_next ? (const char*)g.Bt + (size_t)nxt.pn * tstep : cB;
;         for (int t = 0; t < nt; t += 2) {
;             const bool last = (t == nt - 2);
;             const char* a1 = cA + (size_t)(t + 1) * kstepA;
;             const char* a2 = last ? nA : cA + (size_t)(t + 2) * kstepA; const char* b2 = last ? nB : cB + (size_t)(t + 2) * kstep;
;             const char* a3 = a2 + kstepA; const char* b3 = b2 + kstep;
;             if (last && has_next) S.a_ready(nxt);
;             if constexpr (SP2) {
;             PG8_LDB(B0, 0, 0); PG8_LDB(B1, 0, 1); PG8_SCHED; PG8_LDA(At, 0, 0); PG8_STAGE(PG8_SA(1, 1), a1 + hstepA, voffA);
;             PG8_WAIT_V(8); PG8_WAIT_L(0); PG8_BAR; PG8_MMA(0, 0, At, B0); PG8_MMA(0, 1, At, B1); PG8_BAR; PG8_SCHED;
;             PG8_LDA(At, 0, 1); PG8_STAGE(PG8_SB(0, 0), b2, voffB); PG8_STAGE(PG8_SB(0, 1), b2 + hstep, voffB); PG8_STAGE(PG8_SA(0, 0), a2, voffA);
.LBB0_132:
	s_ashr_i32 s43, s42, 31
	s_lshl_b64 s[44:45], s[42:43], 19
	s_add_u32 s44, s26, s44
	s_addc_u32 s45, s27, s45
	s_and_b64 s[46:47], s[0:1], exec
	s_cselect_b32 s43, s45, s61
	s_cselect_b32 s83, s44, s60
	s_ashr_i32 s41, s40, 31
	s_lshl_b64 s[46:47], s[40:41], 19
	s_add_u32 s46, s6, s46
	s_addc_u32 s47, s7, s47
	s_and_b64 s[64:65], s[0:1], exec
	s_cselect_b32 s41, s47, s63
	s_cselect_b32 s84, s46, s62
	s_add_u32 s60, s60, 0x40080
	s_addc_u32 s61, s61, 0
	s_add_u32 s85, s62, 0x100
	s_addc_u32 s86, s63, 0
	s_mov_b32 s87, -2
	ds_read_b128 v[150:153], v156
	ds_read_b128 v[162:165], v156 offset:1024
	ds_read_b128 v[166:169], v156 offset:2048
	ds_read_b128 v[170:173], v156 offset:3072
	ds_read_b128 v[174:177], v157
	ds_read_b128 v[178:181], v157 offset:1024
	ds_read_b128 v[182:185], v157 offset:2048
	ds_read_b128 v[186:189], v157 offset:3072
	s_add_u32 s62, s60, 0xfffc0080
	s_addc_u32 s63, s61, -1
	s_cmp_eq_u32 s87, 12
	s_cselect_b32 s65, s43, s63
	s_cselect_b32 s64, s83, s62
	s_cselect_b32 s63, s41, s86
	s_cselect_b32 s62, s84, s85
	v_lshl_add_u64 v[224:225], s[60:61], 0, v[140:141]
	s_add_i32 m0, s49, 0xc000
	ds_read_b128 v[190:193], v158
	ds_read_b128 v[194:197], v158 offset:1024
	ds_read_b128 v[200:203], v158 offset:2048
	ds_read_b128 v[204:207], v158 offset:3072
	ds_read_b128 v[208:211], v158 offset:4096
	ds_read_b128 v[212:215], v158 offset:5120
	ds_read_b128 v[216:219], v158 offset:6144
	ds_read_b128 v[220:223], v158 offset:7168
	global_load_lds_dwordx4 v[224:225], off
	v_lshl_add_u64 v[224:225], s[60:61], 0, v[142:143]
	s_add_i32 m0, s49, 0xe000
	s_nop 0
	global_load_lds_dwordx4 v[224:225], off
	s_waitcnt vmcnt(8)
	s_waitcnt lgkmcnt(0)
	s_barrier
	s_setprio 1
	s_waitcnt lgkmcnt(0)
	v_mfma_f32_16x16x32_bf16 v[124:127], v[150:153], v[190:193], 0
	v_mfma_f32_16x16x32_bf16 v[120:123], v[166:169], v[190:193], 0
	v_mfma_f32_16x16x32_bf16 v[108:111], v[150:153], v[200:203], 0
	v_mfma_f32_16x16x32_bf16 v[104:107], v[166:169], v[200:203], 0
	v_mfma_f32_16x16x32_bf16 v[92:95], v[150:153], v[208:211], 0
	v_mfma_f32_16x16x32_bf16 v[88:91], v[166:169], v[208:211], 0
	v_mfma_f32_16x16x32_bf16 v[76:79], v[150:153], v[216:219], 0
	v_mfma_f32_16x16x32_bf16 v[72:75], v[166:169], v[216:219], 0
	v_mfma_f32_16x16x32_bf16 v[124:127], v[162:165], v[194:197], v[124:127]
	v_mfma_f32_16x16x32_bf16 v[120:123], v[170:173], v[194:197], v[120:123]
	v_mfma_f32_16x16x32_bf16 v[108:111], v[162:165], v[204:207], v[108:111]
	v_mfma_f32_16x16x32_bf16 v[104:107], v[170:173], v[204:207], v[104:107]
	v_mfma_f32_16x16x32_bf16 v[92:95], v[162:165], v[212:215], v[92:95]
	v_mfma_f32_16x16x32_bf16 v[88:91], v[170:173], v[212:215], v[88:91]
	v_mfma_f32_16x16x32_bf16 v[76:79], v[162:165], v[220:223], v[76:79]
	v_mfma_f32_16x16x32_bf16 v[72:75], v[170:173], v[220:223], v[72:75]
	s_setprio 0
	s_setprio 1
	v_mfma_f32_16x16x32_bf16 v[116:119], v[174:177], v[190:193], 0
	v_mfma_f32_16x16x32_bf16 v[112:115], v[182:185], v[190:193], 0
	v_mfma_f32_16x16x32_bf16 v[100:103], v[174:177], v[200:203], 0
	v_mfma_f32_16x16x32_bf16 v[96:99], v[182:185], v[200:203], 0
	v_mfma_f32_16x16x32_bf16 v[84:87], v[174:177], v[208:211], 0
	v_mfma_f32_16x16x32_bf16 v[80:83], v[182:185], v[208:211], 0
	v_mfma_f32_16x16x32_bf16 v[68:71], v[174:177], v[216:219], 0
	v_mfma_f32_16x16x32_bf16 v[64:67], v[182:185], v[216:219], 0
	v_mfma_f32_16x16x32_bf16 v[116:119], v[178:181], v[194:197], v[116:119]
	v_mfma_f32_16x16x32_bf16 v[112:115], v[186:189], v[194:197], v[112:115]
	v_mfma_f32_16x16x32_bf16 v[100:103], v[178:181], v[204:207], v[100:103]
	v_mfma_f32_16x16x32_bf16 v[96:99], v[186:189], v[204:207], v[96:99]
	v_mfma_f32_16x16x32_bf16 v[84:87], v[178:181], v[212:215], v[84:87]
	v_mfma_f32_16x16x32_bf16 v[80:83], v[186:189], v[212:215], v[80:83]
	v_mfma_f32_16x16x32_bf16 v[68:71], v[178:181], v[220:223], v[68:71]
	v_mfma_f32_16x16x32_bf16 v[64:67], v[186:189], v[220:223], v[64:67]
	s_setprio 0
	s_barrier
	s_add_i32 s88, s78, s66
	v_lshl_add_u64 v[224:225], s[62:63], 0, v[130:131]
	s_mov_b32 m0, s88
	ds_read_b128 v[190:193], v158 offset:16384
	ds_read_b128 v[194:197], v158 offset:17408
	ds_read_b128 v[200:203], v158 offset:18432
	ds_read_b128 v[204:207], v158 offset:19456
	ds_read_b128 v[208:211], v158 offset:20480
	ds_read_b128 v[212:215], v158 offset:21504
	ds_read_b128 v[216:219], v158 offset:22528
	ds_read_b128 v[220:223], v158 offset:23552
	global_load_lds_dwordx4 v[224:225], off
	s_add_i32 m0, s88, 0x2000
	s_add_u32 s88, s62, 0x40000
	v_lshl_add_u64 v[226:227], s[62:63], 0, v[134:135]
	s_addc_u32 s89, s63, 0
	s_add_i32 s90, s79, s66
	global_load_lds_dwordx4 v[226:227], off
	v_lshl_add_u64 v[228:229], s[88:89], 0, v[130:131]
	s_mov_b32 m0, s90
	v_lshl_add_u64 v[230:231], s[64:65], 0, v[132:133]
	global_load_lds_dwordx4 v[228:229], off
	v_lshl_add_u64 v[228:229], s[88:89], 0, v[134:135]
	s_add_i32 m0, s90, 0x2000
	s_nop 0
	global_load_lds_dwordx4 v[228:229], off
	v_lshl_add_u64 v[228:229], s[64:65], 0, v[128:129]
	s_mov_b32 m0, s49
	s_nop 0
	global_load_lds_dwordx4 v[228:229], off
	s_mov_b32 m0, s68
	s_nop 0
	global_load_lds_dwordx4 v[230:231], off
	s_waitcnt vmcnt(8)
	s_waitcnt lgkmcnt(0)
	s_barrier
; #define PG8_STAGE(bufoff, gbase, voff) do { _Pragma("unroll") for (int _i = 0; _i < 2; ++_i) \
;         __builtin_amdgcn_global_load_lds((const unsigned*)((const char*)(gbase) + (voff)[_i]), (PG8_LAS unsigned*)(lds + (bufoff) + ldsw + _i * 8192), 16, 0, 0); } while (0)
; #define PG8_LDA(dst, b, h) do { _Pragma("unroll") for (int m = 0; m < 4; ++m) _Pragma("unroll") for (int k = 0; k < 2; ++k) dst[m][k] = *(const PG8_LAS bf16x8*)(lds + PG8_SA(b, h) + aoff + m * 2048 + k * 1024); } while (0)
; #define PG8_LDB(dst, b, h) do { _Pragma("unroll") for (int n = 0; n < 2; ++n) _Pragma("unroll") for (int k = 0; k < 2; ++k) dst[n][k] = *(const PG8_LAS bf16x8*)(lds + PG8_SB(b, h) + boff + n * 2048 + k * 1024); } while (0)
; #define PG8_MMA(ai, bj, At, Bt) do { __builtin_amdgcn_s_setprio(1); _Pragma("unroll") for (int m = 0; m < 4; ++m) _Pragma("unroll") for (int n = 0; n < 2; ++n) _Pragma("unroll") for (int k = 0; k < 2; ++k) \
;         acc[ai][bj][m][n] = __builtin_amdgcn_mfma_f32_16x16x32_bf16(Bt[n][k], At[m][k], acc[ai][bj][m][n], 0, 0, 0); __builtin_amdgcn_s_setprio(0); } while (0)
; #define PG8_WAIT_V(n) asm volatile("s_waitcnt vmcnt(" #n ")" ::: "memory")
; #define PG8_WAIT_L(n) asm volatile("s_waitcnt lgkmcnt(" #n ")" ::: "memory")
; #define PG8_BAR __builtin_amdgcn_s_barrier()
; #define PG8_SCHED __builtin_amdgcn_sched_barrier(0)
; template <class Epi, class Sched, bool ALIGN_EPI = false, bool SP2 = false, bool ATILED = false>
; __device__ __forceinline__ void gemm_phase(PG8_LAS unsigned char* lds, const Gemm g, const Sched& S, const Epi& E) {
;     ...
;             PG8_WAIT_V(8); PG8_WAIT_L(0); PG8_BAR; PG8_MMA(1, 0, At, B0); PG8_MMA(1, 1, At, B1); PG8_BAR; PG8_SCHED;
;             PG8_LDB(B0, 1, 0); PG8_LDB(B1, 1, 1); PG8_SCHED; PG8_LDA(At, 1, 0); PG8_STAGE(PG8_SA(0, 1), a2 + hstepA, voffA);
;             PG8_WAIT_V(8); PG8_WAIT_L(0); PG8_BAR; PG8_MMA(0, 0, At, B0); PG8_MMA(0, 1, At, B1); PG8_BAR; PG8_SCHED;
	s_setprio 1
	s_waitcnt lgkmcnt(0)
	v_mfma_f32_16x16x32_bf16 v[60:63], v[150:153], v[190:193], 0
	v_mfma_f32_16x16x32_bf16 v[56:59], v[166:169], v[190:193], 0
	v_mfma_f32_16x16x32_bf16 v[44:47], v[150:153], v[200:203], 0
	v_mfma_f32_16x16x32_bf16 v[40:43], v[166:169], v[200:203], 0
	v_mfma_f32_16x16x32_bf16 v[28:31], v[150:153], v[208:211], 0
	v_mfma_f32_16x16x32_bf16 v[24:27], v[166:169], v[208:211], 0
	v_mfma_f32_16x16x32_bf16 v[12:15], v[150:153], v[216:219], 0
	v_mfma_f32_16x16x32_bf16 v[8:11], v[166:169], v[216:219], 0
	v_mfma_f32_16x16x32_bf16 v[60:63], v[162:165], v[194:197], v[60:63]
	v_mfma_f32_16x16x32_bf16 v[56:59], v[170:173], v[194:197], v[56:59]
	v_mfma_f32_16x16x32_bf16 v[44:47], v[162:165], v[204:207], v[44:47]
	v_mfma_f32_16x16x32_bf16 v[40:43], v[170:173], v[204:207], v[40:43]
	v_mfma_f32_16x16x32_bf16 v[28:31], v[162:165], v[212:215], v[28:31]
	v_mfma_f32_16x16x32_bf16 v[24:27], v[170:173], v[212:215], v[24:27]
	v_mfma_f32_16x16x32_bf16 v[12:15], v[162:165], v[220:223], v[12:15]
	v_mfma_f32_16x16x32_bf16 v[8:11], v[170:173], v[220:223], v[8:11]
	s_setprio 0
	s_setprio 1
	v_mfma_f32_16x16x32_bf16 v[52:55], v[174:177], v[190:193], 0
	v_mfma_f32_16x16x32_bf16 v[48:51], v[182:185], v[190:193], 0
	v_mfma_f32_16x16x32_bf16 v[36:39], v[174:177], v[200:203], 0
	v_mfma_f32_16x16x32_bf16 v[32:35], v[182:185], v[200:203], 0
	v_mfma_f32_16x16x32_bf16 v[20:23], v[174:177], v[208:211], 0
	v_mfma_f32_16x16x32_bf16 v[16:19], v[182:185], v[208:211], 0
	v_mfma_f32_16x16x32_bf16 v[4:7], v[174:177], v[216:219], 0
	v_mfma_f32_16x16x32_bf16 v[0:3], v[182:185], v[216:219], 0
	v_mfma_f32_16x16x32_bf16 v[52:55], v[178:181], v[194:197], v[52:55]
	v_mfma_f32_16x16x32_bf16 v[48:51], v[186:189], v[194:197], v[48:51]
	v_mfma_f32_16x16x32_bf16 v[36:39], v[178:181], v[204:207], v[36:39]
	v_mfma_f32_16x16x32_bf16 v[32:35], v[186:189], v[204:207], v[32:35]
	v_mfma_f32_16x16x32_bf16 v[20:23], v[178:181], v[212:215], v[20:23]
	v_mfma_f32_16x16x32_bf16 v[16:19], v[186:189], v[212:215], v[16:19]
	v_mfma_f32_16x16x32_bf16 v[4:7], v[178:181], v[220:223], v[4:7]
	v_mfma_f32_16x16x32_bf16 v[0:3], v[186:189], v[220:223], v[0:3]
	s_setprio 0
	s_barrier
	s_add_i32 s88, 0, 0x18000
	v_add_u32_e32 v136, s88, v155
	s_add_i32 s89, 0, 0x1c000
	ds_read_b128 v[150:153], v136
	ds_read_b128 v[162:165], v136 offset:1024
	ds_read_b128 v[166:169], v136 offset:2048
	ds_read_b128 v[170:173], v136 offset:3072
	v_add_u32_e32 v136, s89, v155
	ds_read_b128 v[174:177], v136
	ds_read_b128 v[178:181], v136 offset:1024
	ds_read_b128 v[182:185], v136 offset:2048
	ds_read_b128 v[186:189], v136 offset:3072
	s_add_u32 s64, s64, 0x40000
	s_addc_u32 s65, s65, 0
	s_mov_b32 m0, s69
	v_lshl_add_u64 v[232:233], s[64:65], 0, v[128:129]
	ds_read_b128 v[190:193], v158 offset:32768
	ds_read_b128 v[194:197], v158 offset:33792
	ds_read_b128 v[200:203], v158 offset:34816
	ds_read_b128 v[204:207], v158 offset:35840
	ds_read_b128 v[208:211], v158 offset:36864
	ds_read_b128 v[212:215], v158 offset:37888
	ds_read_b128 v[216:219], v158 offset:38912
	ds_read_b128 v[220:223], v158 offset:39936
	global_load_lds_dwordx4 v[232:233], off
	v_lshl_add_u64 v[232:233], s[64:65], 0, v[132:133]
	s_mov_b32 m0, s70
	s_nop 0
	global_load_lds_dwordx4 v[232:233], off
	s_waitcnt vmcnt(8)
	s_waitcnt lgkmcnt(0)
	s_barrier
	s_setprio 1
	s_waitcnt lgkmcnt(0)
	v_mfma_f32_16x16x32_bf16 v[124:127], v[150:153], v[190:193], v[124:127]
	v_mfma_f32_16x16x32_bf16 v[120:123], v[166:169], v[190:193], v[120:123]
	v_mfma_f32_16x16x32_bf16 v[108:111], v[150:153], v[200:203], v[108:111]
	v_mfma_f32_16x16x32_bf16 v[104:107], v[166:169], v[200:203], v[104:107]
	v_mfma_f32_16x16x32_bf16 v[92:95], v[150:153], v[208:211], v[92:95]
	v_mfma_f32_16x16x32_bf16 v[88:91], v[166:169], v[208:211], v[88:91]
	v_mfma_f32_16x16x32_bf16 v[76:79], v[150:153], v[216:219], v[76:79]
	v_mfma_f32_16x16x32_bf16 v[72:75], v[166:169], v[216:219], v[72:75]
	v_mfma_f32_16x16x32_bf16 v[124:127], v[162:165], v[194:197], v[124:127]
	v_mfma_f32_16x16x32_bf16 v[120:123], v[170:173], v[194:197], v[120:123]
	v_mfma_f32_16x16x32_bf16 v[108:111], v[162:165], v[204:207], v[108:111]
	v_mfma_f32_16x16x32_bf16 v[104:107], v[170:173], v[204:207], v[104:107]
	v_mfma_f32_16x16x32_bf16 v[92:95], v[162:165], v[212:215], v[92:95]
	v_mfma_f32_16x16x32_bf16 v[88:91], v[170:173], v[212:215], v[88:91]
	v_mfma_f32_16x16x32_bf16 v[76:79], v[162:165], v[220:223], v[76:79]
	v_mfma_f32_16x16x32_bf16 v[72:75], v[170:173], v[220:223], v[72:75]
	s_setprio 0
	s_setprio 1
	v_mfma_f32_16x16x32_bf16 v[116:119], v[174:177], v[190:193], v[116:119]
	v_mfma_f32_16x16x32_bf16 v[112:115], v[182:185], v[190:193], v[112:115]
	v_mfma_f32_16x16x32_bf16 v[100:103], v[174:177], v[200:203], v[100:103]
	v_mfma_f32_16x16x32_bf16 v[96:99], v[182:185], v[200:203], v[96:99]
	v_mfma_f32_16x16x32_bf16 v[84:87], v[174:177], v[208:211], v[84:87]
	v_mfma_f32_16x16x32_bf16 v[80:83], v[182:185], v[208:211], v[80:83]
	v_mfma_f32_16x16x32_bf16 v[68:71], v[174:177], v[216:219], v[68:71]
	v_mfma_f32_16x16x32_bf16 v[64:67], v[182:185], v[216:219], v[64:67]
	v_mfma_f32_16x16x32_bf16 v[116:119], v[178:181], v[194:197], v[116:119]
	v_mfma_f32_16x16x32_bf16 v[112:115], v[186:189], v[194:197], v[112:115]
	v_mfma_f32_16x16x32_bf16 v[100:103], v[178:181], v[204:207], v[100:103]
	v_mfma_f32_16x16x32_bf16 v[96:99], v[186:189], v[204:207], v[96:99]
	v_mfma_f32_16x16x32_bf16 v[84:87], v[178:181], v[212:215], v[84:87]
	v_mfma_f32_16x16x32_bf16 v[80:83], v[186:189], v[212:215], v[80:83]
	v_mfma_f32_16x16x32_bf16 v[68:71], v[178:181], v[220:223], v[68:71]
	v_mfma_f32_16x16x32_bf16 v[64:67], v[186:189], v[220:223], v[64:67]
	s_setprio 0
	s_barrier
; #define PG8_STAGE(bufoff, gbase, voff) do { _Pragma("unroll") for (int _i = 0; _i < 2; ++_i) \
;         __builtin_amdgcn_global_load_lds((const unsigned*)((const char*)(gbase) + (voff)[_i]), (PG8_LAS unsigned*)(lds + (bufoff) + ldsw + _i * 8192), 16, 0, 0); } while (0)
; #define PG8_LDA(dst, b, h) do { _Pragma("unroll") for (int m = 0; m < 4; ++m) _Pragma("unroll") for (int k = 0; k < 2; ++k) dst[m][k] = *(const PG8_LAS bf16x8*)(lds + PG8_SA(b, h) + aoff + m * 2048 + k * 1024); } while (0)
; #define PG8_MMA(ai, bj, At, Bt) do { __builtin_amdgcn_s_setprio(1); _Pragma("unroll") for (int m = 0; m < 4; ++m) _Pragma("unroll") for (int n = 0; n < 2; ++n) _Pragma("unroll") for (int k = 0; k < 2; ++k) \
;         acc[ai][bj][m][n] = __builtin_amdgcn_mfma_f32_16x16x32_bf16(Bt[n][k], At[m][k], acc[ai][bj][m][n], 0, 0, 0); __builtin_amdgcn_s_setprio(0); } while (0)
; #define PG8_WAIT_V(n) asm volatile("s_waitcnt vmcnt(" #n ")" ::: "memory")
; #define PG8_WAIT_L(n) asm volatile("s_waitcnt lgkmcnt(" #n ")" ::: "memory")
; #define PG8_BAR __builtin_amdgcn_s_barrier()
; #define PG8_SCHED __builtin_amdgcn_sched_barrier(0)
; template <class Epi, class Sched, bool ALIGN_EPI = false, bool SP2 = false, bool ATILED = false>
; __device__ __forceinline__ void gemm_phase(PG8_LAS unsigned char* lds, const Gemm g, const Sched& S, const Epi& E) {
;     ...
;         for (int t = 0; t < nt; t += 2) {
;     ...
;             PG8_LDA(At, 1, 1); PG8_STAGE(PG8_SB(1, 0), b3, voffB); PG8_STAGE(PG8_SB(1, 1), b3 + hstep, voffB); PG8_STAGE(PG8_SA(1, 0), a3, voffA);
;             PG8_WAIT_V(8); PG8_WAIT_L(0); PG8_BAR; PG8_MMA(1, 0, At, B0); PG8_MMA(1, 1, At, B1); PG8_BAR; PG8_SCHED;
	s_add_i32 s64, s88, s66
	v_lshl_add_u64 v[224:225], v[224:225], 0, s[8:9]
	s_mov_b32 m0, s64
	ds_read_b128 v[190:193], v158 offset:49152
	ds_read_b128 v[194:197], v158 offset:50176
	ds_read_b128 v[200:203], v158 offset:51200
	ds_read_b128 v[204:207], v158 offset:52224
	ds_read_b128 v[208:211], v158 offset:53248
	ds_read_b128 v[212:215], v158 offset:54272
	ds_read_b128 v[216:219], v158 offset:55296
	ds_read_b128 v[220:223], v158 offset:56320
	global_load_lds_dwordx4 v[224:225], off
	s_add_i32 m0, s64, 0x2000
	s_add_u32 s62, s62, 0x40080
	v_lshl_add_u64 v[224:225], v[226:227], 0, s[8:9]
	s_addc_u32 s63, s63, 0
	s_add_i32 s64, s89, s66
	global_load_lds_dwordx4 v[224:225], off
	v_lshl_add_u64 v[224:225], s[62:63], 0, v[130:131]
	s_mov_b32 m0, s64
	s_nop 0
	global_load_lds_dwordx4 v[224:225], off
	v_lshl_add_u64 v[224:225], s[62:63], 0, v[134:135]
	s_add_i32 m0, s64, 0x2000
	s_nop 0
	global_load_lds_dwordx4 v[224:225], off
	v_lshl_add_u64 v[224:225], v[228:229], 0, s[8:9]
	s_mov_b32 m0, s76
	s_nop 0
	global_load_lds_dwordx4 v[224:225], off
	v_lshl_add_u64 v[224:225], v[230:231], 0, s[8:9]
	s_mov_b32 m0, s77
	s_nop 0
	global_load_lds_dwordx4 v[224:225], off
	s_waitcnt vmcnt(8)
	s_waitcnt lgkmcnt(0)
	s_barrier
	s_setprio 1
	s_waitcnt lgkmcnt(0)
	v_mfma_f32_16x16x32_bf16 v[60:63], v[150:153], v[190:193], v[60:63]
	v_mfma_f32_16x16x32_bf16 v[56:59], v[166:169], v[190:193], v[56:59]
	v_mfma_f32_16x16x32_bf16 v[44:47], v[150:153], v[200:203], v[44:47]
	v_mfma_f32_16x16x32_bf16 v[40:43], v[166:169], v[200:203], v[40:43]
	v_mfma_f32_16x16x32_bf16 v[28:31], v[150:153], v[208:211], v[28:31]
	v_mfma_f32_16x16x32_bf16 v[24:27], v[166:169], v[208:211], v[24:27]
	v_mfma_f32_16x16x32_bf16 v[12:15], v[150:153], v[216:219], v[12:15]
	v_mfma_f32_16x16x32_bf16 v[8:11], v[166:169], v[216:219], v[8:11]
	v_mfma_f32_16x16x32_bf16 v[60:63], v[162:165], v[194:197], v[60:63]
	v_mfma_f32_16x16x32_bf16 v[56:59], v[170:173], v[194:197], v[56:59]
	v_mfma_f32_16x16x32_bf16 v[44:47], v[162:165], v[204:207], v[44:47]
	v_mfma_f32_16x16x32_bf16 v[40:43], v[170:173], v[204:207], v[40:43]
	v_mfma_f32_16x16x32_bf16 v[28:31], v[162:165], v[212:215], v[28:31]
	v_mfma_f32_16x16x32_bf16 v[24:27], v[170:173], v[212:215], v[24:27]
	v_mfma_f32_16x16x32_bf16 v[12:15], v[162:165], v[220:223], v[12:15]
	v_mfma_f32_16x16x32_bf16 v[8:11], v[170:173], v[220:223], v[8:11]
	s_setprio 0
	s_setprio 1
	v_mfma_f32_16x16x32_bf16 v[52:55], v[174:177], v[190:193], v[52:55]
	v_mfma_f32_16x16x32_bf16 v[48:51], v[182:185], v[190:193], v[48:51]
	v_mfma_f32_16x16x32_bf16 v[36:39], v[174:177], v[200:203], v[36:39]
	v_mfma_f32_16x16x32_bf16 v[32:35], v[182:185], v[200:203], v[32:35]
	v_mfma_f32_16x16x32_bf16 v[20:23], v[174:177], v[208:211], v[20:23]
	v_mfma_f32_16x16x32_bf16 v[16:19], v[182:185], v[208:211], v[16:19]
	v_mfma_f32_16x16x32_bf16 v[4:7], v[174:177], v[216:219], v[4:7]
	v_mfma_f32_16x16x32_bf16 v[0:3], v[182:185], v[216:219], v[0:3]
	v_mfma_f32_16x16x32_bf16 v[52:55], v[178:181], v[194:197], v[52:55]
	v_mfma_f32_16x16x32_bf16 v[48:51], v[186:189], v[194:197], v[48:51]
	v_mfma_f32_16x16x32_bf16 v[36:39], v[178:181], v[204:207], v[36:39]
	v_mfma_f32_16x16x32_bf16 v[32:35], v[186:189], v[204:207], v[32:35]
	v_mfma_f32_16x16x32_bf16 v[20:23], v[178:181], v[212:215], v[20:23]
	v_mfma_f32_16x16x32_bf16 v[16:19], v[186:189], v[212:215], v[16:19]
	v_mfma_f32_16x16x32_bf16 v[4:7], v[178:181], v[220:223], v[4:7]
	v_mfma_f32_16x16x32_bf16 v[0:3], v[186:189], v[220:223], v[0:3]
	s_setprio 0
	s_barrier
	s_add_i32 s87, s87, 2
	s_add_u32 s60, s60, 0x100
	s_addc_u32 s61, s61, 0
	s_add_u32 s85, s85, 0x100
	s_addc_u32 s86, s86, 0
	s_cmp_gt_u32 s87, 13

; #define PG8_STAGE(bufoff, gbase, voff) do { _Pragma("unroll") for (int _i = 0; _i < 2; ++_i) \
;         __builtin_amdgcn_global_load_lds((const unsigned*)((const char*)(gbase) + (voff)[_i]), (PG8_LAS unsigned*)(lds + (bufoff) + ldsw + _i * 8192), 16, 0, 0); } while (0)
; #define PG8_LDA(dst, b, h) do { _Pragma("unroll") for (int m = 0; m < 4; ++m) _Pragma("unroll") for (int k = 0; k < 2; ++k) dst[m][k] = *(const PG8_LAS bf16x8*)(lds + PG8_SA(b, h) + aoff + m * 2048 + k * 1024); } while (0)
; #define PG8_LDB(dst, b, h) do { _Pragma("unroll") for (int n = 0; n < 2; ++n) _Pragma("unroll") for (int k = 0; k < 2; ++k) dst[n][k] = *(const PG8_LAS bf16x8*)(lds + PG8_SB(b, h) + boff + n * 2048 + k * 1024); } while (0)
; #define PG8_MMA(ai, bj, At, Bt) do { __builtin_amdgcn_s_setprio(1); _Pragma("unroll") for (int m = 0; m < 4; ++m) _Pragma("unroll") for (int n = 0; n < 2; ++n) _Pragma("unroll") for (int k = 0; k < 2; ++k) \
;         acc[ai][bj][m][n] = __builtin_amdgcn_mfma_f32_16x16x32_bf16(Bt[n][k], At[m][k], acc[ai][bj][m][n], 0, 0, 0); __builtin_amdgcn_s_setprio(0); } while (0)
; #define PG8_WAIT_V(n) asm volatile("s_waitcnt vmcnt(" #n ")" ::: "memory")
; template <class Epi, class Sched, bool ALIGN_EPI = false, bool SP2 = false, bool ATILED = false>
; __device__ __forceinline__ void gemm_phase(PG8_LAS unsigned char* lds, const Gemm g, const Sched& S, const Epi& E) {
;     ...
;         const char* nA = has_next ? (const char*)g.A + (size_t)nxt.pm * tstepA : cA; const char* nB = has_next ? (const char*)g.Bt + (size_t)nxt.pn * tstep : cB;
;         for (int t = 0; t < nt; t += 2) {
;             const bool last = (t == nt - 2);
;             const char* a1 = cA + (size_t)(t + 1) * kstepA;
;             const char* a2 = last ? nA : cA + (size_t)(t + 2) * kstepA; const char* b2 = last ? nB : cB + (size_t)(t + 2) * kstep;
;             const char* a3 = a2 + kstepA; const char* b3 = b2 + kstep;
;             if (last && has_next) S.a_ready(nxt);
;             if constexpr (SP2) {
;             PG8_LDB(B0, 0, 0); PG8_LDB(B1, 0, 1); PG8_SCHED; PG8_LDA(At, 0, 0); PG8_STAGE(PG8_SA(1, 1), a1 + hstepA, voffA);
;             PG8_WAIT_V(8); PG8_WAIT_L(0); PG8_BAR; PG8_MMA(0, 0, At, B0); PG8_MMA(0, 1, At, B1); PG8_BAR; PG8_SCHED;
;             PG8_LDA(At, 0, 1); PG8_STAGE(PG8_SB(0, 0), b2, voffB); PG8_STAGE(PG8_SB(0, 1), b2 + hstep, voffB); PG8_STAGE(PG8_SA(0, 0), a2, voffA);
.LBB0_210:
	s_add_u32 s79, s46, 0x100
	s_addc_u32 s80, s47, 0
	s_add_u32 s46, s48, 0xc000
	s_addc_u32 s47, s49, 0
	s_mov_b32 s81, -2
	s_waitcnt lgkmcnt(0)
	ds_read_b128 v[128:131], v189
	ds_read_b128 v[132:135], v189 offset:1024
	ds_read_b128 v[136:139], v189 offset:2048
	ds_read_b128 v[140:143], v189 offset:3072
	ds_read_b128 v[144:147], v190
	ds_read_b128 v[148:151], v190 offset:1024
	ds_read_b128 v[168:171], v190 offset:2048
	ds_read_b128 v[172:175], v190 offset:3072
	s_add_u32 s48, s46, 0x4000
	s_addc_u32 s49, s47, 0
	s_cmp_eq_u32 s81, 40
	s_cselect_b32 s62, s4, s48
	s_cselect_b32 s63, s5, s49
	s_cselect_b32 s60, s44, s79
	s_cselect_b32 s61, s45, s80
	s_add_u32 s48, s62, 0x8000
	s_addc_u32 s49, s63, 0
	v_lshl_add_u64 v[184:185], s[46:47], 0, v[160:161]
	s_add_i32 m0, s65, 0xc000
	ds_read_b128 v[176:179], v191
	ds_read_b128 v[180:183], v191 offset:1024
	ds_read_b128 v[194:197], v191 offset:2048
	ds_read_b128 v[200:203], v191 offset:3072
	ds_read_b128 v[204:207], v191 offset:4096
	ds_read_b128 v[208:211], v191 offset:5120
	ds_read_b128 v[212:215], v191 offset:6144
	ds_read_b128 v[216:219], v191 offset:7168
	global_load_lds_dwordx4 v[184:185], off
	v_lshl_add_u64 v[184:185], s[46:47], 0, v[162:163]
	s_add_i32 m0, s65, 0xe000
	s_nop 0
	global_load_lds_dwordx4 v[184:185], off
	s_waitcnt vmcnt(8)
	s_waitcnt lgkmcnt(0)
	s_barrier
	s_setprio 1
	s_waitcnt lgkmcnt(0)
	v_mfma_f32_16x16x32_bf16 v[124:127], v[128:131], v[176:179], 0
	v_mfma_f32_16x16x32_bf16 v[120:123], v[136:139], v[176:179], 0
	v_mfma_f32_16x16x32_bf16 v[108:111], v[128:131], v[194:197], 0
	v_mfma_f32_16x16x32_bf16 v[104:107], v[136:139], v[194:197], 0
	v_mfma_f32_16x16x32_bf16 v[92:95], v[128:131], v[204:207], 0
	v_mfma_f32_16x16x32_bf16 v[88:91], v[136:139], v[204:207], 0
	v_mfma_f32_16x16x32_bf16 v[76:79], v[128:131], v[212:215], 0
	v_mfma_f32_16x16x32_bf16 v[72:75], v[136:139], v[212:215], 0
	v_mfma_f32_16x16x32_bf16 v[124:127], v[132:135], v[180:183], v[124:127]
	v_mfma_f32_16x16x32_bf16 v[120:123], v[140:143], v[180:183], v[120:123]
	v_mfma_f32_16x16x32_bf16 v[108:111], v[132:135], v[200:203], v[108:111]
	v_mfma_f32_16x16x32_bf16 v[104:107], v[140:143], v[200:203], v[104:107]
	v_mfma_f32_16x16x32_bf16 v[92:95], v[132:135], v[208:211], v[92:95]
	v_mfma_f32_16x16x32_bf16 v[88:91], v[140:143], v[208:211], v[88:91]
	v_mfma_f32_16x16x32_bf16 v[76:79], v[132:135], v[216:219], v[76:79]
	v_mfma_f32_16x16x32_bf16 v[72:75], v[140:143], v[216:219], v[72:75]
	s_setprio 0
	s_setprio 1
	v_mfma_f32_16x16x32_bf16 v[116:119], v[144:147], v[176:179], 0
	v_mfma_f32_16x16x32_bf16 v[112:115], v[168:171], v[176:179], 0
	v_mfma_f32_16x16x32_bf16 v[100:103], v[144:147], v[194:197], 0
	v_mfma_f32_16x16x32_bf16 v[96:99], v[168:171], v[194:197], 0
	v_mfma_f32_16x16x32_bf16 v[84:87], v[144:147], v[204:207], 0
	v_mfma_f32_16x16x32_bf16 v[80:83], v[168:171], v[204:207], 0
	v_mfma_f32_16x16x32_bf16 v[68:71], v[144:147], v[212:215], 0
	v_mfma_f32_16x16x32_bf16 v[64:67], v[168:171], v[212:215], 0
	v_mfma_f32_16x16x32_bf16 v[116:119], v[148:151], v[180:183], v[116:119]
	v_mfma_f32_16x16x32_bf16 v[112:115], v[172:175], v[180:183], v[112:115]
	v_mfma_f32_16x16x32_bf16 v[100:103], v[148:151], v[200:203], v[100:103]
	v_mfma_f32_16x16x32_bf16 v[96:99], v[172:175], v[200:203], v[96:99]
	v_mfma_f32_16x16x32_bf16 v[84:87], v[148:151], v[208:211], v[84:87]
	v_mfma_f32_16x16x32_bf16 v[80:83], v[172:175], v[208:211], v[80:83]
	v_mfma_f32_16x16x32_bf16 v[68:71], v[148:151], v[216:219], v[68:71]
	v_mfma_f32_16x16x32_bf16 v[64:67], v[172:175], v[216:219], v[64:67]
	s_setprio 0
	s_barrier
	s_add_i32 s83, s73, s64
	v_lshl_add_u64 v[184:185], s[60:61], 0, v[154:155]
	s_mov_b32 m0, s83
	ds_read_b128 v[176:179], v191 offset:16384
	ds_read_b128 v[180:183], v191 offset:17408
	ds_read_b128 v[194:197], v191 offset:18432
	ds_read_b128 v[200:203], v191 offset:19456
	ds_read_b128 v[204:207], v191 offset:20480
	ds_read_b128 v[208:211], v191 offset:21504
	ds_read_b128 v[212:215], v191 offset:22528
	ds_read_b128 v[216:219], v191 offset:23552
	global_load_lds_dwordx4 v[184:185], off
	s_add_i32 m0, s83, 0x2000
	s_add_u32 s84, s60, 0xb0000
	v_lshl_add_u64 v[220:221], s[60:61], 0, v[158:159]
	s_addc_u32 s85, s61, 0
	s_add_i32 s83, s74, s64
	global_load_lds_dwordx4 v[220:221], off
	v_lshl_add_u64 v[222:223], s[84:85], 0, v[154:155]
	s_mov_b32 m0, s83
	s_nop 0
	global_load_lds_dwordx4 v[222:223], off
	v_lshl_add_u64 v[222:223], s[84:85], 0, v[158:159]
	s_add_i32 m0, s83, 0x2000
	s_nop 0
	global_load_lds_dwordx4 v[222:223], off
	v_lshl_add_u64 v[222:223], s[62:63], 0, v[152:153]
	s_mov_b32 m0, s65
	s_nop 0
	global_load_lds_dwordx4 v[222:223], off
	v_lshl_add_u64 v[222:223], s[62:63], 0, v[156:157]
	s_mov_b32 m0, s66
	s_nop 0
	global_load_lds_dwordx4 v[222:223], off
	s_waitcnt vmcnt(8)
	s_waitcnt lgkmcnt(0)
	s_barrier
; #define PG8_STAGE(bufoff, gbase, voff) do { _Pragma("unroll") for (int _i = 0; _i < 2; ++_i) \
;         __builtin_amdgcn_global_load_lds((const unsigned*)((const char*)(gbase) + (voff)[_i]), (PG8_LAS unsigned*)(lds + (bufoff) + ldsw + _i * 8192), 16, 0, 0); } while (0)
; #define PG8_LDA(dst, b, h) do { _Pragma("unroll") for (int m = 0; m < 4; ++m) _Pragma("unroll") for (int k = 0; k < 2; ++k) dst[m][k] = *(const PG8_LAS bf16x8*)(lds + PG8_SA(b, h) + aoff + m * 2048 + k * 1024); } while (0)
; #define PG8_LDB(dst, b, h) do { _Pragma("unroll") for (int n = 0; n < 2; ++n) _Pragma("unroll") for (int k = 0; k < 2; ++k) dst[n][k] = *(const PG8_LAS bf16x8*)(lds + PG8_SB(b, h) + boff + n * 2048 + k * 1024); } while (0)
; #define PG8_MMA(ai, bj, At, Bt) do { __builtin_amdgcn_s_setprio(1); _Pragma("unroll") for (int m = 0; m < 4; ++m) _Pragma("unroll") for (int n = 0; n < 2; ++n) _Pragma("unroll") for (int k = 0; k < 2; ++k) \
;         acc[ai][bj][m][n] = __builtin_amdgcn_mfma_f32_16x16x32_bf16(Bt[n][k], At[m][k], acc[ai][bj][m][n], 0, 0, 0); __builtin_amdgcn_s_setprio(0); } while (0)
; #define PG8_WAIT_V(n) asm volatile("s_waitcnt vmcnt(" #n ")" ::: "memory")
; #define PG8_WAIT_L(n) asm volatile("s_waitcnt lgkmcnt(" #n ")" ::: "memory")
; #define PG8_BAR __builtin_amdgcn_s_barrier()
; #define PG8_SCHED __builtin_amdgcn_sched_barrier(0)
; template <class Epi, class Sched, bool ALIGN_EPI = false, bool SP2 = false, bool ATILED = false>
; __device__ __forceinline__ void gemm_phase(PG8_LAS unsigned char* lds, const Gemm g, const Sched& S, const Epi& E) {
;     ...
;             PG8_WAIT_V(8); PG8_WAIT_L(0); PG8_BAR; PG8_MMA(1, 0, At, B0); PG8_MMA(1, 1, At, B1); PG8_BAR; PG8_SCHED;
;             PG8_LDB(B0, 1, 0); PG8_LDB(B1, 1, 1); PG8_SCHED; PG8_LDA(At, 1, 0); PG8_STAGE(PG8_SA(0, 1), a2 + hstepA, voffA);
;             PG8_WAIT_V(8); PG8_WAIT_L(0); PG8_BAR; PG8_MMA(0, 0, At, B0); PG8_MMA(0, 1, At, B1); PG8_BAR; PG8_SCHED;
	s_setprio 1
	s_waitcnt lgkmcnt(0)
	v_mfma_f32_16x16x32_bf16 v[60:63], v[128:131], v[176:179], 0
	v_mfma_f32_16x16x32_bf16 v[56:59], v[136:139], v[176:179], 0
	v_mfma_f32_16x16x32_bf16 v[44:47], v[128:131], v[194:197], 0
	v_mfma_f32_16x16x32_bf16 v[40:43], v[136:139], v[194:197], 0
	v_mfma_f32_16x16x32_bf16 v[28:31], v[128:131], v[204:207], 0
	v_mfma_f32_16x16x32_bf16 v[24:27], v[136:139], v[204:207], 0
	v_mfma_f32_16x16x32_bf16 v[12:15], v[128:131], v[212:215], 0
	v_mfma_f32_16x16x32_bf16 v[8:11], v[136:139], v[212:215], 0
	v_mfma_f32_16x16x32_bf16 v[60:63], v[132:135], v[180:183], v[60:63]
	v_mfma_f32_16x16x32_bf16 v[56:59], v[140:143], v[180:183], v[56:59]
	v_mfma_f32_16x16x32_bf16 v[44:47], v[132:135], v[200:203], v[44:47]
	v_mfma_f32_16x16x32_bf16 v[40:43], v[140:143], v[200:203], v[40:43]
	v_mfma_f32_16x16x32_bf16 v[28:31], v[132:135], v[208:211], v[28:31]
	v_mfma_f32_16x16x32_bf16 v[24:27], v[140:143], v[208:211], v[24:27]
	v_mfma_f32_16x16x32_bf16 v[12:15], v[132:135], v[216:219], v[12:15]
	v_mfma_f32_16x16x32_bf16 v[8:11], v[140:143], v[216:219], v[8:11]
	s_setprio 0
	s_setprio 1
	v_mfma_f32_16x16x32_bf16 v[52:55], v[144:147], v[176:179], 0
	v_mfma_f32_16x16x32_bf16 v[48:51], v[168:171], v[176:179], 0
	v_mfma_f32_16x16x32_bf16 v[36:39], v[144:147], v[194:197], 0
	v_mfma_f32_16x16x32_bf16 v[32:35], v[168:171], v[194:197], 0
	v_mfma_f32_16x16x32_bf16 v[20:23], v[144:147], v[204:207], 0
	v_mfma_f32_16x16x32_bf16 v[16:19], v[168:171], v[204:207], 0
	v_mfma_f32_16x16x32_bf16 v[4:7], v[144:147], v[212:215], 0
	v_mfma_f32_16x16x32_bf16 v[0:3], v[168:171], v[212:215], 0
	v_mfma_f32_16x16x32_bf16 v[52:55], v[148:151], v[180:183], v[52:55]
	v_mfma_f32_16x16x32_bf16 v[48:51], v[172:175], v[180:183], v[48:51]
	v_mfma_f32_16x16x32_bf16 v[36:39], v[148:151], v[200:203], v[36:39]
	v_mfma_f32_16x16x32_bf16 v[32:35], v[172:175], v[200:203], v[32:35]
	v_mfma_f32_16x16x32_bf16 v[20:23], v[148:151], v[208:211], v[20:23]
	v_mfma_f32_16x16x32_bf16 v[16:19], v[172:175], v[208:211], v[16:19]
	v_mfma_f32_16x16x32_bf16 v[4:7], v[148:151], v[216:219], v[4:7]
	v_mfma_f32_16x16x32_bf16 v[0:3], v[172:175], v[216:219], v[0:3]
	s_setprio 0
	s_barrier
	s_add_i32 s83, 0, 0x18000
	s_add_i32 s84, 0, 0x1c000
	v_add_u32_e32 v140, s83, v187
	v_add_u32_e32 v172, s84, v187
	ds_read_b128 v[128:131], v140
	ds_read_b128 v[132:135], v140 offset:1024
	ds_read_b128 v[136:139], v140 offset:2048
	ds_read_b128 v[140:143], v140 offset:3072
	ds_read_b128 v[144:147], v172
	ds_read_b128 v[148:151], v172 offset:1024
	ds_read_b128 v[168:171], v172 offset:2048
	ds_read_b128 v[172:175], v172 offset:3072
	s_add_u32 s62, s62, 0x4000
	s_addc_u32 s63, s63, 0
	s_mov_b32 m0, s67
	v_lshl_add_u64 v[222:223], s[62:63], 0, v[152:153]
	ds_read_b128 v[176:179], v191 offset:32768
	ds_read_b128 v[180:183], v191 offset:33792
	ds_read_b128 v[194:197], v191 offset:34816
	ds_read_b128 v[200:203], v191 offset:35840
	ds_read_b128 v[204:207], v191 offset:36864
	ds_read_b128 v[208:211], v191 offset:37888
	ds_read_b128 v[212:215], v191 offset:38912
	ds_read_b128 v[216:219], v191 offset:39936
	global_load_lds_dwordx4 v[222:223], off
	v_lshl_add_u64 v[222:223], s[62:63], 0, v[156:157]
	s_mov_b32 m0, s68
	s_nop 0
	global_load_lds_dwordx4 v[222:223], off
	s_waitcnt vmcnt(8)
	s_waitcnt lgkmcnt(0)
	s_barrier
	s_setprio 1
	s_waitcnt lgkmcnt(0)
	v_mfma_f32_16x16x32_bf16 v[124:127], v[128:131], v[176:179], v[124:127]
	v_mfma_f32_16x16x32_bf16 v[120:123], v[136:139], v[176:179], v[120:123]
	v_mfma_f32_16x16x32_bf16 v[108:111], v[128:131], v[194:197], v[108:111]
	v_mfma_f32_16x16x32_bf16 v[104:107], v[136:139], v[194:197], v[104:107]
	v_mfma_f32_16x16x32_bf16 v[92:95], v[128:131], v[204:207], v[92:95]
	v_mfma_f32_16x16x32_bf16 v[88:91], v[136:139], v[204:207], v[88:91]
	v_mfma_f32_16x16x32_bf16 v[76:79], v[128:131], v[212:215], v[76:79]
	v_mfma_f32_16x16x32_bf16 v[72:75], v[136:139], v[212:215], v[72:75]
	v_mfma_f32_16x16x32_bf16 v[124:127], v[132:135], v[180:183], v[124:127]
	v_mfma_f32_16x16x32_bf16 v[120:123], v[140:143], v[180:183], v[120:123]
	v_mfma_f32_16x16x32_bf16 v[108:111], v[132:135], v[200:203], v[108:111]
	v_mfma_f32_16x16x32_bf16 v[104:107], v[140:143], v[200:203], v[104:107]
	v_mfma_f32_16x16x32_bf16 v[92:95], v[132:135], v[208:211], v[92:95]
	v_mfma_f32_16x16x32_bf16 v[88:91], v[140:143], v[208:211], v[88:91]
	v_mfma_f32_16x16x32_bf16 v[76:79], v[132:135], v[216:219], v[76:79]
	v_mfma_f32_16x16x32_bf16 v[72:75], v[140:143], v[216:219], v[72:75]
	s_setprio 0
	s_setprio 1
	v_mfma_f32_16x16x32_bf16 v[116:119], v[144:147], v[176:179], v[116:119]
	v_mfma_f32_16x16x32_bf16 v[112:115], v[168:171], v[176:179], v[112:115]
	v_mfma_f32_16x16x32_bf16 v[100:103], v[144:147], v[194:197], v[100:103]
	v_mfma_f32_16x16x32_bf16 v[96:99], v[168:171], v[194:197], v[96:99]
	v_mfma_f32_16x16x32_bf16 v[84:87], v[144:147], v[204:207], v[84:87]
	v_mfma_f32_16x16x32_bf16 v[80:83], v[168:171], v[204:207], v[80:83]
	v_mfma_f32_16x16x32_bf16 v[68:71], v[144:147], v[212:215], v[68:71]
	v_mfma_f32_16x16x32_bf16 v[64:67], v[168:171], v[212:215], v[64:67]
	v_mfma_f32_16x16x32_bf16 v[116:119], v[148:151], v[180:183], v[116:119]
	v_mfma_f32_16x16x32_bf16 v[112:115], v[172:175], v[180:183], v[112:115]
	v_mfma_f32_16x16x32_bf16 v[100:103], v[148:151], v[200:203], v[100:103]
	v_mfma_f32_16x16x32_bf16 v[96:99], v[172:175], v[200:203], v[96:99]
	v_mfma_f32_16x16x32_bf16 v[84:87], v[148:151], v[208:211], v[84:87]
	v_mfma_f32_16x16x32_bf16 v[80:83], v[172:175], v[208:211], v[80:83]
	v_mfma_f32_16x16x32_bf16 v[68:71], v[148:151], v[216:219], v[68:71]
	v_mfma_f32_16x16x32_bf16 v[64:67], v[172:175], v[216:219], v[64:67]
	s_setprio 0
	s_barrier
; #define PG8_STAGE(bufoff, gbase, voff) do { _Pragma("unroll") for (int _i = 0; _i < 2; ++_i) \
;         __builtin_amdgcn_global_load_lds((const unsigned*)((const char*)(gbase) + (voff)[_i]), (PG8_LAS unsigned*)(lds + (bufoff) + ldsw + _i * 8192), 16, 0, 0); } while (0)
; #define PG8_LDA(dst, b, h) do { _Pragma("unroll") for (int m = 0; m < 4; ++m) _Pragma("unroll") for (int k = 0; k < 2; ++k) dst[m][k] = *(const PG8_LAS bf16x8*)(lds + PG8_SA(b, h) + aoff + m * 2048 + k * 1024); } while (0)
; #define PG8_MMA(ai, bj, At, Bt) do { __builtin_amdgcn_s_setprio(1); _Pragma("unroll") for (int m = 0; m < 4; ++m) _Pragma("unroll") for (int n = 0; n < 2; ++n) _Pragma("unroll") for (int k = 0; k < 2; ++k) \
;         acc[ai][bj][m][n] = __builtin_amdgcn_mfma_f32_16x16x32_bf16(Bt[n][k], At[m][k], acc[ai][bj][m][n], 0, 0, 0); __builtin_amdgcn_s_setprio(0); } while (0)
; #define PG8_WAIT_V(n) asm volatile("s_waitcnt vmcnt(" #n ")" ::: "memory")
; #define PG8_WAIT_L(n) asm volatile("s_waitcnt lgkmcnt(" #n ")" ::: "memory")
; #define PG8_BAR __builtin_amdgcn_s_barrier()
; #define PG8_SCHED __builtin_amdgcn_sched_barrier(0)
; template <class Epi, class Sched, bool ALIGN_EPI = false, bool SP2 = false, bool ATILED = false>
; __device__ __forceinline__ void gemm_phase(PG8_LAS unsigned char* lds, const Gemm g, const Sched& S, const Epi& E) {
;     ...
;         for (int t = 0; t < nt; t += 2) {
;     ...
;             PG8_LDA(At, 1, 1); PG8_STAGE(PG8_SB(1, 0), b3, voffB); PG8_STAGE(PG8_SB(1, 1), b3 + hstep, voffB); PG8_STAGE(PG8_SA(1, 0), a3, voffA);
;             PG8_WAIT_V(8); PG8_WAIT_L(0); PG8_BAR; PG8_MMA(1, 0, At, B0); PG8_MMA(1, 1, At, B1); PG8_BAR; PG8_SCHED;
	s_add_i32 s62, s83, s64
	v_lshl_add_u64 v[184:185], v[184:185], 0, s[40:41]
	s_mov_b32 m0, s62
	ds_read_b128 v[176:179], v191 offset:49152
	ds_read_b128 v[180:183], v191 offset:50176
	ds_read_b128 v[194:197], v191 offset:51200
	ds_read_b128 v[200:203], v191 offset:52224
	ds_read_b128 v[204:207], v191 offset:53248
	ds_read_b128 v[208:211], v191 offset:54272
	ds_read_b128 v[212:215], v191 offset:55296
	ds_read_b128 v[216:219], v191 offset:56320
	global_load_lds_dwordx4 v[184:185], off
	s_add_i32 m0, s62, 0x2000
	s_add_u32 s60, s60, 0xb0080
	v_lshl_add_u64 v[184:185], v[220:221], 0, s[40:41]
	s_addc_u32 s61, s61, 0
	s_add_i32 s62, s84, s64
	global_load_lds_dwordx4 v[184:185], off
	v_lshl_add_u64 v[184:185], s[60:61], 0, v[154:155]
	s_mov_b32 m0, s62
	s_nop 0
	global_load_lds_dwordx4 v[184:185], off
	v_lshl_add_u64 v[184:185], s[60:61], 0, v[158:159]
	s_add_i32 m0, s62, 0x2000
	s_nop 0
	global_load_lds_dwordx4 v[184:185], off
	v_lshl_add_u64 v[184:185], s[48:49], 0, v[152:153]
	s_mov_b32 m0, s71
	s_nop 0
	global_load_lds_dwordx4 v[184:185], off
	v_lshl_add_u64 v[184:185], s[48:49], 0, v[156:157]
	s_mov_b32 m0, s72
	s_nop 0
	global_load_lds_dwordx4 v[184:185], off
	s_waitcnt vmcnt(8)
	s_waitcnt lgkmcnt(0)
	s_barrier
	s_setprio 1
	s_waitcnt lgkmcnt(0)
	v_mfma_f32_16x16x32_bf16 v[60:63], v[128:131], v[176:179], v[60:63]
	v_mfma_f32_16x16x32_bf16 v[56:59], v[136:139], v[176:179], v[56:59]
	v_mfma_f32_16x16x32_bf16 v[44:47], v[128:131], v[194:197], v[44:47]
	v_mfma_f32_16x16x32_bf16 v[40:43], v[136:139], v[194:197], v[40:43]
	v_mfma_f32_16x16x32_bf16 v[28:31], v[128:131], v[204:207], v[28:31]
	v_mfma_f32_16x16x32_bf16 v[24:27], v[136:139], v[204:207], v[24:27]
	v_mfma_f32_16x16x32_bf16 v[12:15], v[128:131], v[212:215], v[12:15]
	v_mfma_f32_16x16x32_bf16 v[8:11], v[136:139], v[212:215], v[8:11]
	v_mfma_f32_16x16x32_bf16 v[60:63], v[132:135], v[180:183], v[60:63]
	v_mfma_f32_16x16x32_bf16 v[56:59], v[140:143], v[180:183], v[56:59]
	v_mfma_f32_16x16x32_bf16 v[44:47], v[132:135], v[200:203], v[44:47]
	v_mfma_f32_16x16x32_bf16 v[40:43], v[140:143], v[200:203], v[40:43]
	v_mfma_f32_16x16x32_bf16 v[28:31], v[132:135], v[208:211], v[28:31]
	v_mfma_f32_16x16x32_bf16 v[24:27], v[140:143], v[208:211], v[24:27]
	v_mfma_f32_16x16x32_bf16 v[12:15], v[132:135], v[216:219], v[12:15]
	v_mfma_f32_16x16x32_bf16 v[8:11], v[140:143], v[216:219], v[8:11]
	s_setprio 0
	s_setprio 1
	v_mfma_f32_16x16x32_bf16 v[52:55], v[144:147], v[176:179], v[52:55]
	v_mfma_f32_16x16x32_bf16 v[48:51], v[168:171], v[176:179], v[48:51]
	v_mfma_f32_16x16x32_bf16 v[36:39], v[144:147], v[194:197], v[36:39]
	v_mfma_f32_16x16x32_bf16 v[32:35], v[168:171], v[194:197], v[32:35]
	v_mfma_f32_16x16x32_bf16 v[20:23], v[144:147], v[204:207], v[20:23]
	v_mfma_f32_16x16x32_bf16 v[16:19], v[168:171], v[204:207], v[16:19]
	v_mfma_f32_16x16x32_bf16 v[4:7], v[144:147], v[212:215], v[4:7]
	v_mfma_f32_16x16x32_bf16 v[0:3], v[168:171], v[212:215], v[0:3]
	v_mfma_f32_16x16x32_bf16 v[52:55], v[148:151], v[180:183], v[52:55]
	v_mfma_f32_16x16x32_bf16 v[48:51], v[172:175], v[180:183], v[48:51]
	v_mfma_f32_16x16x32_bf16 v[36:39], v[148:151], v[200:203], v[36:39]
	v_mfma_f32_16x16x32_bf16 v[32:35], v[172:175], v[200:203], v[32:35]
	v_mfma_f32_16x16x32_bf16 v[20:23], v[148:151], v[208:211], v[20:23]
	v_mfma_f32_16x16x32_bf16 v[16:19], v[172:175], v[208:211], v[16:19]
	v_mfma_f32_16x16x32_bf16 v[4:7], v[148:151], v[216:219], v[4:7]
	v_mfma_f32_16x16x32_bf16 v[0:3], v[172:175], v[216:219], v[0:3]
	s_setprio 0
	s_barrier
	s_add_i32 s81, s81, 2
	s_add_u32 s79, s79, 0x100
	s_addc_u32 s80, s80, 0
	s_add_u32 s46, s46, 0x10000
	s_addc_u32 s47, s47, 0
	s_cmp_gt_u32 s81, 41

; #define PG8_STAGE(bufoff, gbase, voff) do { _Pragma("unroll") for (int _i = 0; _i < 2; ++_i) \
;         __builtin_amdgcn_global_load_lds((const unsigned*)((const char*)(gbase) + (voff)[_i]), (PG8_LAS unsigned*)(lds + (bufoff) + ldsw + _i * 8192), 16, 0, 0); } while (0)
; #define PG8_LDA(dst, b, h) do { _Pragma("unroll") for (int m = 0; m < 4; ++m) _Pragma("unroll") for (int k = 0; k < 2; ++k) dst[m][k] = *(const PG8_LAS bf16x8*)(lds + PG8_SA(b, h) + aoff + m * 2048 + k * 1024); } while (0)
; #define PG8_LDB(dst, b, h) do { _Pragma("unroll") for (int n = 0; n < 2; ++n) _Pragma("unroll") for (int k = 0; k < 2; ++k) dst[n][k] = *(const PG8_LAS bf16x8*)(lds + PG8_SB(b, h) + boff + n * 2048 + k * 1024); } while (0)
; #define PG8_MMA(ai, bj, At, Bt) do { __builtin_amdgcn_s_setprio(1); _Pragma("unroll") for (int m = 0; m < 4; ++m) _Pragma("unroll") for (int n = 0; n < 2; ++n) _Pragma("unroll") for (int k = 0; k < 2; ++k) \
;         acc[ai][bj][m][n] = __builtin_amdgcn_mfma_f32_16x16x32_bf16(Bt[n][k], At[m][k], acc[ai][bj][m][n], 0, 0, 0); __builtin_amdgcn_s_setprio(0); } while (0)
; template <class Epi, class Sched, bool ALIGN_EPI = false, bool SP2 = false, bool ATILED = false>
; __device__ __forceinline__ void gemm_phase(PG8_LAS unsigned char* lds, const Gemm g, const Sched& S, const Epi& E) {
;     ...
;         const bool has_next = S.next(ui + 1, nxt);
;         const char* nA = has_next ? (const char*)g.A + (size_t)nxt.pm * tstepA : cA; const char* nB = has_next ? (const char*)g.Bt + (size_t)nxt.pn * tstep : cB;
;         for (int t = 0; t < nt; t += 2) {
;             const bool last = (t == nt - 2);
;             const char* a1 = cA + (size_t)(t + 1) * kstepA;
;             const char* a2 = last ? nA : cA + (size_t)(t + 2) * kstepA; const char* b2 = last ? nB : cB + (size_t)(t + 2) * kstep;
;             const char* a3 = a2 + kstepA; const char* b3 = b2 + kstep;
;             if (last && has_next) S.a_ready(nxt);
;             if constexpr (SP2) {
;             PG8_LDB(B0, 0, 0); PG8_LDB(B1, 0, 1); PG8_SCHED; PG8_LDA(At, 0, 0); PG8_STAGE(PG8_SA(1, 1), a1 + hstepA, voffA);
;             PG8_WAIT_V(8); PG8_WAIT_L(0); PG8_BAR; PG8_MMA(0, 0, At, B0); PG8_MMA(0, 1, At, B1); PG8_BAR; PG8_SCHED;
;             PG8_LDA(At, 0, 1); PG8_STAGE(PG8_SB(0, 0), b2, voffB); PG8_STAGE(PG8_SB(0, 1), b2 + hstep, voffB); PG8_STAGE(PG8_SA(0, 0), a2, voffA);
.LBB0_299:
	s_ashr_i32 s49, s48, 31
	s_lshl_b64 s[58:59], s[48:49], 19
	s_add_u32 s58, s26, s58
	s_addc_u32 s59, s27, s59
	s_and_b64 s[60:61], s[0:1], exec
	s_cselect_b32 s5, s59, s65
	s_cselect_b32 s6, s58, s64
	s_ashr_i32 s47, s46, 31
	s_lshl_b64 s[60:61], s[46:47], 19
	s_add_u32 s60, s54, s60
	s_addc_u32 s61, s55, s61
	s_and_b64 s[68:69], s[0:1], exec
	s_cselect_b32 s45, s61, s67
	s_cselect_b32 s47, s60, s66
	s_add_u32 s64, s64, 0x40080
	s_addc_u32 s65, s65, 0
	s_add_u32 s49, s66, 0x100
	s_addc_u32 s63, s67, 0
	s_mov_b32 s83, -2
	ds_read_b128 v[156:159], v201
	ds_read_b128 v[160:163], v201 offset:1024
	ds_read_b128 v[164:167], v201 offset:2048
	ds_read_b128 v[168:171], v201 offset:3072
	ds_read_b128 v[172:175], v202
	ds_read_b128 v[176:179], v202 offset:1024
	ds_read_b128 v[180:183], v202 offset:2048
	ds_read_b128 v[184:187], v202 offset:3072
	s_add_u32 s66, s64, 0xfffc0080
	s_addc_u32 s67, s65, -1
	s_cmp_eq_u32 s83, 12
	s_cselect_b32 s69, s5, s67
	s_cselect_b32 s68, s6, s66
	s_cselect_b32 s67, s45, s63
	s_cselect_b32 s66, s47, s49
	v_lshl_add_u64 v[196:197], s[64:65], 0, v[146:147]
	s_add_i32 m0, s71, 0xc000
	ds_read_b128 v[188:191], v203
	ds_read_b128 v[192:195], v203 offset:1024
	ds_read_b128 v[208:211], v203 offset:2048
	ds_read_b128 v[212:215], v203 offset:3072
	ds_read_b128 v[216:219], v203 offset:4096
	ds_read_b128 v[220:223], v203 offset:5120
	ds_read_b128 v[224:227], v203 offset:6144
	ds_read_b128 v[228:231], v203 offset:7168
	global_load_lds_dwordx4 v[196:197], off
	v_lshl_add_u64 v[196:197], s[64:65], 0, v[148:149]
	s_add_i32 m0, s71, 0xe000
	s_nop 0
	global_load_lds_dwordx4 v[196:197], off
	s_waitcnt vmcnt(8)
	s_waitcnt lgkmcnt(0)
	s_barrier
	s_setprio 1
	s_waitcnt lgkmcnt(0)
	v_mfma_f32_16x16x32_bf16 v[124:127], v[156:159], v[188:191], 0
	v_mfma_f32_16x16x32_bf16 v[120:123], v[164:167], v[188:191], 0
	v_mfma_f32_16x16x32_bf16 v[116:119], v[156:159], v[208:211], 0
	v_mfma_f32_16x16x32_bf16 v[112:115], v[164:167], v[208:211], 0
	v_mfma_f32_16x16x32_bf16 v[96:99], v[156:159], v[216:219], 0
	v_mfma_f32_16x16x32_bf16 v[88:91], v[164:167], v[216:219], 0
	v_mfma_f32_16x16x32_bf16 v[80:83], v[156:159], v[224:227], 0
	v_mfma_f32_16x16x32_bf16 v[72:75], v[164:167], v[224:227], 0
	v_mfma_f32_16x16x32_bf16 v[124:127], v[160:163], v[192:195], v[124:127]
	v_mfma_f32_16x16x32_bf16 v[120:123], v[168:171], v[192:195], v[120:123]
	v_mfma_f32_16x16x32_bf16 v[116:119], v[160:163], v[212:215], v[116:119]
	v_mfma_f32_16x16x32_bf16 v[112:115], v[168:171], v[212:215], v[112:115]
	v_mfma_f32_16x16x32_bf16 v[96:99], v[160:163], v[220:223], v[96:99]
	v_mfma_f32_16x16x32_bf16 v[88:91], v[168:171], v[220:223], v[88:91]
	v_mfma_f32_16x16x32_bf16 v[80:83], v[160:163], v[228:231], v[80:83]
	v_mfma_f32_16x16x32_bf16 v[72:75], v[168:171], v[228:231], v[72:75]
	s_setprio 0
	s_setprio 1
	v_mfma_f32_16x16x32_bf16 v[108:111], v[172:175], v[188:191], 0
	v_mfma_f32_16x16x32_bf16 v[104:107], v[180:183], v[188:191], 0
	v_mfma_f32_16x16x32_bf16 v[100:103], v[172:175], v[208:211], 0
	v_mfma_f32_16x16x32_bf16 v[92:95], v[180:183], v[208:211], 0
	v_mfma_f32_16x16x32_bf16 v[84:87], v[172:175], v[216:219], 0
	v_mfma_f32_16x16x32_bf16 v[76:79], v[180:183], v[216:219], 0
	v_mfma_f32_16x16x32_bf16 v[68:71], v[172:175], v[224:227], 0
	v_mfma_f32_16x16x32_bf16 v[64:67], v[180:183], v[224:227], 0
	v_mfma_f32_16x16x32_bf16 v[108:111], v[176:179], v[192:195], v[108:111]
	v_mfma_f32_16x16x32_bf16 v[104:107], v[184:187], v[192:195], v[104:107]
	v_mfma_f32_16x16x32_bf16 v[100:103], v[176:179], v[212:215], v[100:103]
	v_mfma_f32_16x16x32_bf16 v[92:95], v[184:187], v[212:215], v[92:95]
	v_mfma_f32_16x16x32_bf16 v[84:87], v[176:179], v[220:223], v[84:87]
	v_mfma_f32_16x16x32_bf16 v[76:79], v[184:187], v[220:223], v[76:79]
	v_mfma_f32_16x16x32_bf16 v[68:71], v[176:179], v[228:231], v[68:71]
	v_mfma_f32_16x16x32_bf16 v[64:67], v[184:187], v[228:231], v[64:67]
	s_setprio 0
	s_barrier
	s_add_i32 s84, s79, s70
	v_lshl_add_u64 v[196:197], s[66:67], 0, v[130:131]
	s_mov_b32 m0, s84
	ds_read_b128 v[188:191], v203 offset:16384
	ds_read_b128 v[192:195], v203 offset:17408
	ds_read_b128 v[208:211], v203 offset:18432
	ds_read_b128 v[212:215], v203 offset:19456
	ds_read_b128 v[216:219], v203 offset:20480
	ds_read_b128 v[220:223], v203 offset:21504
	ds_read_b128 v[224:227], v203 offset:22528
	ds_read_b128 v[228:231], v203 offset:23552
	global_load_lds_dwordx4 v[196:197], off
	s_add_i32 m0, s84, 0x2000
	s_add_u32 s84, s66, 0x40000
	v_lshl_add_u64 v[232:233], s[66:67], 0, v[134:135]
	s_addc_u32 s85, s67, 0
	s_add_i32 s86, s80, s70
	global_load_lds_dwordx4 v[232:233], off
	v_lshl_add_u64 v[234:235], s[84:85], 0, v[130:131]
	s_mov_b32 m0, s86
	v_lshl_add_u64 v[236:237], s[68:69], 0, v[132:133]
	global_load_lds_dwordx4 v[234:235], off
	v_lshl_add_u64 v[234:235], s[84:85], 0, v[134:135]
	s_add_i32 m0, s86, 0x2000
	s_nop 0
	global_load_lds_dwordx4 v[234:235], off
	v_lshl_add_u64 v[234:235], s[68:69], 0, v[128:129]
	s_mov_b32 m0, s71
	s_nop 0
	global_load_lds_dwordx4 v[234:235], off
	s_mov_b32 m0, s72
	s_nop 0
	global_load_lds_dwordx4 v[236:237], off
	s_waitcnt vmcnt(8)
	s_waitcnt lgkmcnt(0)
	s_barrier
; #define PG8_STAGE(bufoff, gbase, voff) do { _Pragma("unroll") for (int _i = 0; _i < 2; ++_i) \
;         __builtin_amdgcn_global_load_lds((const unsigned*)((const char*)(gbase) + (voff)[_i]), (PG8_LAS unsigned*)(lds + (bufoff) + ldsw + _i * 8192), 16, 0, 0); } while (0)
; #define PG8_LDA(dst, b, h) do { _Pragma("unroll") for (int m = 0; m < 4; ++m) _Pragma("unroll") for (int k = 0; k < 2; ++k) dst[m][k] = *(const PG8_LAS bf16x8*)(lds + PG8_SA(b, h) + aoff + m * 2048 + k * 1024); } while (0)
; #define PG8_LDB(dst, b, h) do { _Pragma("unroll") for (int n = 0; n < 2; ++n) _Pragma("unroll") for (int k = 0; k < 2; ++k) dst[n][k] = *(const PG8_LAS bf16x8*)(lds + PG8_SB(b, h) + boff + n * 2048 + k * 1024); } while (0)
; #define PG8_MMA(ai, bj, At, Bt) do { __builtin_amdgcn_s_setprio(1); _Pragma("unroll") for (int m = 0; m < 4; ++m) _Pragma("unroll") for (int n = 0; n < 2; ++n) _Pragma("unroll") for (int k = 0; k < 2; ++k) \
;         acc[ai][bj][m][n] = __builtin_amdgcn_mfma_f32_16x16x32_bf16(Bt[n][k], At[m][k], acc[ai][bj][m][n], 0, 0, 0); __builtin_amdgcn_s_setprio(0); } while (0)
; #define PG8_WAIT_V(n) asm volatile("s_waitcnt vmcnt(" #n ")" ::: "memory")
; #define PG8_WAIT_L(n) asm volatile("s_waitcnt lgkmcnt(" #n ")" ::: "memory")
; #define PG8_BAR __builtin_amdgcn_s_barrier()
; #define PG8_SCHED __builtin_amdgcn_sched_barrier(0)
; template <class Epi, class Sched, bool ALIGN_EPI = false, bool SP2 = false, bool ATILED = false>
; __device__ __forceinline__ void gemm_phase(PG8_LAS unsigned char* lds, const Gemm g, const Sched& S, const Epi& E) {
;     ...
;             PG8_WAIT_V(8); PG8_WAIT_L(0); PG8_BAR; PG8_MMA(1, 0, At, B0); PG8_MMA(1, 1, At, B1); PG8_BAR; PG8_SCHED;
;             PG8_LDB(B0, 1, 0); PG8_LDB(B1, 1, 1); PG8_SCHED; PG8_LDA(At, 1, 0); PG8_STAGE(PG8_SA(0, 1), a2 + hstepA, voffA);
;             PG8_WAIT_V(8); PG8_WAIT_L(0); PG8_BAR; PG8_MMA(0, 0, At, B0); PG8_MMA(0, 1, At, B1); PG8_BAR; PG8_SCHED;
	s_setprio 1
	s_waitcnt lgkmcnt(0)
	v_mfma_f32_16x16x32_bf16 v[60:63], v[156:159], v[188:191], 0
	v_mfma_f32_16x16x32_bf16 v[56:59], v[164:167], v[188:191], 0
	v_mfma_f32_16x16x32_bf16 v[48:51], v[156:159], v[208:211], 0
	v_mfma_f32_16x16x32_bf16 v[40:43], v[164:167], v[208:211], 0
	v_mfma_f32_16x16x32_bf16 v[32:35], v[156:159], v[216:219], 0
	v_mfma_f32_16x16x32_bf16 v[24:27], v[164:167], v[216:219], 0
	v_mfma_f32_16x16x32_bf16 v[16:19], v[156:159], v[224:227], 0
	v_mfma_f32_16x16x32_bf16 v[8:11], v[164:167], v[224:227], 0
	v_mfma_f32_16x16x32_bf16 v[60:63], v[160:163], v[192:195], v[60:63]
	v_mfma_f32_16x16x32_bf16 v[56:59], v[168:171], v[192:195], v[56:59]
	v_mfma_f32_16x16x32_bf16 v[48:51], v[160:163], v[212:215], v[48:51]
	v_mfma_f32_16x16x32_bf16 v[40:43], v[168:171], v[212:215], v[40:43]
	v_mfma_f32_16x16x32_bf16 v[32:35], v[160:163], v[220:223], v[32:35]
	v_mfma_f32_16x16x32_bf16 v[24:27], v[168:171], v[220:223], v[24:27]
	v_mfma_f32_16x16x32_bf16 v[16:19], v[160:163], v[228:231], v[16:19]
	v_mfma_f32_16x16x32_bf16 v[8:11], v[168:171], v[228:231], v[8:11]
	s_setprio 0
	s_setprio 1
	v_mfma_f32_16x16x32_bf16 v[52:55], v[172:175], v[188:191], 0
	v_mfma_f32_16x16x32_bf16 v[44:47], v[180:183], v[188:191], 0
	v_mfma_f32_16x16x32_bf16 v[36:39], v[172:175], v[208:211], 0
	v_mfma_f32_16x16x32_bf16 v[28:31], v[180:183], v[208:211], 0
	v_mfma_f32_16x16x32_bf16 v[20:23], v[172:175], v[216:219], 0
	v_mfma_f32_16x16x32_bf16 v[12:15], v[180:183], v[216:219], 0
	v_mfma_f32_16x16x32_bf16 v[4:7], v[172:175], v[224:227], 0
	v_mfma_f32_16x16x32_bf16 v[0:3], v[180:183], v[224:227], 0
	v_mfma_f32_16x16x32_bf16 v[52:55], v[176:179], v[192:195], v[52:55]
	v_mfma_f32_16x16x32_bf16 v[44:47], v[184:187], v[192:195], v[44:47]
	v_mfma_f32_16x16x32_bf16 v[36:39], v[176:179], v[212:215], v[36:39]
	v_mfma_f32_16x16x32_bf16 v[28:31], v[184:187], v[212:215], v[28:31]
	v_mfma_f32_16x16x32_bf16 v[20:23], v[176:179], v[220:223], v[20:23]
	v_mfma_f32_16x16x32_bf16 v[12:15], v[184:187], v[220:223], v[12:15]
	v_mfma_f32_16x16x32_bf16 v[4:7], v[176:179], v[228:231], v[4:7]
	v_mfma_f32_16x16x32_bf16 v[0:3], v[184:187], v[228:231], v[0:3]
	s_setprio 0
	s_barrier
	s_add_i32 s84, 0, 0x18000
	v_add_u32_e32 v136, s84, v200
	s_add_i32 s85, 0, 0x1c000
	ds_read_b128 v[156:159], v136
	ds_read_b128 v[160:163], v136 offset:1024
	ds_read_b128 v[164:167], v136 offset:2048
	ds_read_b128 v[168:171], v136 offset:3072
	v_add_u32_e32 v136, s85, v200
	ds_read_b128 v[172:175], v136
	ds_read_b128 v[176:179], v136 offset:1024
	ds_read_b128 v[180:183], v136 offset:2048
	ds_read_b128 v[184:187], v136 offset:3072
	s_add_u32 s68, s68, 0x40000
	s_addc_u32 s69, s69, 0
	s_mov_b32 m0, s73
	v_lshl_add_u64 v[238:239], s[68:69], 0, v[128:129]
	ds_read_b128 v[188:191], v203 offset:32768
	ds_read_b128 v[192:195], v203 offset:33792
	ds_read_b128 v[208:211], v203 offset:34816
	ds_read_b128 v[212:215], v203 offset:35840
	ds_read_b128 v[216:219], v203 offset:36864
	ds_read_b128 v[220:223], v203 offset:37888
	ds_read_b128 v[224:227], v203 offset:38912
	ds_read_b128 v[228:231], v203 offset:39936
	global_load_lds_dwordx4 v[238:239], off
	v_lshl_add_u64 v[238:239], s[68:69], 0, v[132:133]
	s_mov_b32 m0, s74
	s_nop 0
	global_load_lds_dwordx4 v[238:239], off
	s_waitcnt vmcnt(8)
	s_waitcnt lgkmcnt(0)
	s_barrier
	s_setprio 1
	s_waitcnt lgkmcnt(0)
	v_mfma_f32_16x16x32_bf16 v[124:127], v[156:159], v[188:191], v[124:127]
	v_mfma_f32_16x16x32_bf16 v[120:123], v[164:167], v[188:191], v[120:123]
	v_mfma_f32_16x16x32_bf16 v[116:119], v[156:159], v[208:211], v[116:119]
	v_mfma_f32_16x16x32_bf16 v[112:115], v[164:167], v[208:211], v[112:115]
	v_mfma_f32_16x16x32_bf16 v[96:99], v[156:159], v[216:219], v[96:99]
	v_mfma_f32_16x16x32_bf16 v[88:91], v[164:167], v[216:219], v[88:91]
	v_mfma_f32_16x16x32_bf16 v[80:83], v[156:159], v[224:227], v[80:83]
	v_mfma_f32_16x16x32_bf16 v[72:75], v[164:167], v[224:227], v[72:75]
	v_mfma_f32_16x16x32_bf16 v[124:127], v[160:163], v[192:195], v[124:127]
	v_mfma_f32_16x16x32_bf16 v[120:123], v[168:171], v[192:195], v[120:123]
	v_mfma_f32_16x16x32_bf16 v[116:119], v[160:163], v[212:215], v[116:119]
	v_mfma_f32_16x16x32_bf16 v[112:115], v[168:171], v[212:215], v[112:115]
	v_mfma_f32_16x16x32_bf16 v[96:99], v[160:163], v[220:223], v[96:99]
	v_mfma_f32_16x16x32_bf16 v[88:91], v[168:171], v[220:223], v[88:91]
	v_mfma_f32_16x16x32_bf16 v[80:83], v[160:163], v[228:231], v[80:83]
	v_mfma_f32_16x16x32_bf16 v[72:75], v[168:171], v[228:231], v[72:75]
	s_setprio 0
	s_setprio 1
	v_mfma_f32_16x16x32_bf16 v[108:111], v[172:175], v[188:191], v[108:111]
	v_mfma_f32_16x16x32_bf16 v[104:107], v[180:183], v[188:191], v[104:107]
	v_mfma_f32_16x16x32_bf16 v[100:103], v[172:175], v[208:211], v[100:103]
	v_mfma_f32_16x16x32_bf16 v[92:95], v[180:183], v[208:211], v[92:95]
	v_mfma_f32_16x16x32_bf16 v[84:87], v[172:175], v[216:219], v[84:87]
	v_mfma_f32_16x16x32_bf16 v[76:79], v[180:183], v[216:219], v[76:79]
	v_mfma_f32_16x16x32_bf16 v[68:71], v[172:175], v[224:227], v[68:71]
	v_mfma_f32_16x16x32_bf16 v[64:67], v[180:183], v[224:227], v[64:67]
	v_mfma_f32_16x16x32_bf16 v[108:111], v[176:179], v[192:195], v[108:111]
	v_mfma_f32_16x16x32_bf16 v[104:107], v[184:187], v[192:195], v[104:107]
	v_mfma_f32_16x16x32_bf16 v[100:103], v[176:179], v[212:215], v[100:103]
	v_mfma_f32_16x16x32_bf16 v[92:95], v[184:187], v[212:215], v[92:95]
	v_mfma_f32_16x16x32_bf16 v[84:87], v[176:179], v[220:223], v[84:87]
	v_mfma_f32_16x16x32_bf16 v[76:79], v[184:187], v[220:223], v[76:79]
	v_mfma_f32_16x16x32_bf16 v[68:71], v[176:179], v[228:231], v[68:71]
	v_mfma_f32_16x16x32_bf16 v[64:67], v[184:187], v[228:231], v[64:67]
	s_setprio 0
	s_barrier
; #define PG8_STAGE(bufoff, gbase, voff) do { _Pragma("unroll") for (int _i = 0; _i < 2; ++_i) \
;         __builtin_amdgcn_global_load_lds((const unsigned*)((const char*)(gbase) + (voff)[_i]), (PG8_LAS unsigned*)(lds + (bufoff) + ldsw + _i * 8192), 16, 0, 0); } while (0)
; #define PG8_LDA(dst, b, h) do { _Pragma("unroll") for (int m = 0; m < 4; ++m) _Pragma("unroll") for (int k = 0; k < 2; ++k) dst[m][k] = *(const PG8_LAS bf16x8*)(lds + PG8_SA(b, h) + aoff + m * 2048 + k * 1024); } while (0)
; #define PG8_MMA(ai, bj, At, Bt) do { __builtin_amdgcn_s_setprio(1); _Pragma("unroll") for (int m = 0; m < 4; ++m) _Pragma("unroll") for (int n = 0; n < 2; ++n) _Pragma("unroll") for (int k = 0; k < 2; ++k) \
;         acc[ai][bj][m][n] = __builtin_amdgcn_mfma_f32_16x16x32_bf16(Bt[n][k], At[m][k], acc[ai][bj][m][n], 0, 0, 0); __builtin_amdgcn_s_setprio(0); } while (0)
; #define PG8_WAIT_V(n) asm volatile("s_waitcnt vmcnt(" #n ")" ::: "memory")
; #define PG8_WAIT_L(n) asm volatile("s_waitcnt lgkmcnt(" #n ")" ::: "memory")
; #define PG8_BAR __builtin_amdgcn_s_barrier()
; #define PG8_SCHED __builtin_amdgcn_sched_barrier(0)
; template <class Epi, class Sched, bool ALIGN_EPI = false, bool SP2 = false, bool ATILED = false>
; __device__ __forceinline__ void gemm_phase(PG8_LAS unsigned char* lds, const Gemm g, const Sched& S, const Epi& E) {
;     ...
;         for (int t = 0; t < nt; t += 2) {
;     ...
;             PG8_LDA(At, 1, 1); PG8_STAGE(PG8_SB(1, 0), b3, voffB); PG8_STAGE(PG8_SB(1, 1), b3 + hstep, voffB); PG8_STAGE(PG8_SA(1, 0), a3, voffA);
;             PG8_WAIT_V(8); PG8_WAIT_L(0); PG8_BAR; PG8_MMA(1, 0, At, B0); PG8_MMA(1, 1, At, B1); PG8_BAR; PG8_SCHED;
	s_add_i32 s68, s84, s70
	v_lshl_add_u64 v[196:197], v[196:197], 0, s[38:39]
	s_mov_b32 m0, s68
	ds_read_b128 v[188:191], v203 offset:49152
	ds_read_b128 v[192:195], v203 offset:50176
	ds_read_b128 v[208:211], v203 offset:51200
	ds_read_b128 v[212:215], v203 offset:52224
	ds_read_b128 v[216:219], v203 offset:53248
	ds_read_b128 v[220:223], v203 offset:54272
	ds_read_b128 v[224:227], v203 offset:55296
	ds_read_b128 v[228:231], v203 offset:56320
	global_load_lds_dwordx4 v[196:197], off
	s_add_i32 m0, s68, 0x2000
	s_add_u32 s66, s66, 0x40080
	v_lshl_add_u64 v[196:197], v[232:233], 0, s[38:39]
	s_addc_u32 s67, s67, 0
	s_add_i32 s68, s85, s70
	global_load_lds_dwordx4 v[196:197], off
	v_lshl_add_u64 v[196:197], s[66:67], 0, v[130:131]
	s_mov_b32 m0, s68
	s_nop 0
	global_load_lds_dwordx4 v[196:197], off
	v_lshl_add_u64 v[196:197], s[66:67], 0, v[134:135]
	s_add_i32 m0, s68, 0x2000
	s_nop 0
	global_load_lds_dwordx4 v[196:197], off
	v_lshl_add_u64 v[196:197], v[234:235], 0, s[38:39]
	s_mov_b32 m0, s77
	s_nop 0
	global_load_lds_dwordx4 v[196:197], off
	v_lshl_add_u64 v[196:197], v[236:237], 0, s[38:39]
	s_mov_b32 m0, s78
	s_nop 0
	global_load_lds_dwordx4 v[196:197], off
	s_waitcnt vmcnt(8)
	s_waitcnt lgkmcnt(0)
	s_barrier
	s_setprio 1
	s_waitcnt lgkmcnt(0)
	v_mfma_f32_16x16x32_bf16 v[60:63], v[156:159], v[188:191], v[60:63]
	v_mfma_f32_16x16x32_bf16 v[56:59], v[164:167], v[188:191], v[56:59]
	v_mfma_f32_16x16x32_bf16 v[48:51], v[156:159], v[208:211], v[48:51]
	v_mfma_f32_16x16x32_bf16 v[40:43], v[164:167], v[208:211], v[40:43]
	v_mfma_f32_16x16x32_bf16 v[32:35], v[156:159], v[216:219], v[32:35]
	v_mfma_f32_16x16x32_bf16 v[24:27], v[164:167], v[216:219], v[24:27]
	v_mfma_f32_16x16x32_bf16 v[16:19], v[156:159], v[224:227], v[16:19]
	v_mfma_f32_16x16x32_bf16 v[8:11], v[164:167], v[224:227], v[8:11]
	v_mfma_f32_16x16x32_bf16 v[60:63], v[160:163], v[192:195], v[60:63]
	v_mfma_f32_16x16x32_bf16 v[56:59], v[168:171], v[192:195], v[56:59]
	v_mfma_f32_16x16x32_bf16 v[48:51], v[160:163], v[212:215], v[48:51]
	v_mfma_f32_16x16x32_bf16 v[40:43], v[168:171], v[212:215], v[40:43]
	v_mfma_f32_16x16x32_bf16 v[32:35], v[160:163], v[220:223], v[32:35]
	v_mfma_f32_16x16x32_bf16 v[24:27], v[168:171], v[220:223], v[24:27]
	v_mfma_f32_16x16x32_bf16 v[16:19], v[160:163], v[228:231], v[16:19]
	v_mfma_f32_16x16x32_bf16 v[8:11], v[168:171], v[228:231], v[8:11]
	s_setprio 0
	s_setprio 1
	v_mfma_f32_16x16x32_bf16 v[52:55], v[172:175], v[188:191], v[52:55]
	v_mfma_f32_16x16x32_bf16 v[44:47], v[180:183], v[188:191], v[44:47]
	v_mfma_f32_16x16x32_bf16 v[36:39], v[172:175], v[208:211], v[36:39]
	v_mfma_f32_16x16x32_bf16 v[28:31], v[180:183], v[208:211], v[28:31]
	v_mfma_f32_16x16x32_bf16 v[20:23], v[172:175], v[216:219], v[20:23]
	v_mfma_f32_16x16x32_bf16 v[12:15], v[180:183], v[216:219], v[12:15]
	v_mfma_f32_16x16x32_bf16 v[4:7], v[172:175], v[224:227], v[4:7]
	v_mfma_f32_16x16x32_bf16 v[0:3], v[180:183], v[224:227], v[0:3]
	v_mfma_f32_16x16x32_bf16 v[52:55], v[176:179], v[192:195], v[52:55]
	v_mfma_f32_16x16x32_bf16 v[44:47], v[184:187], v[192:195], v[44:47]
	v_mfma_f32_16x16x32_bf16 v[36:39], v[176:179], v[212:215], v[36:39]
	v_mfma_f32_16x16x32_bf16 v[28:31], v[184:187], v[212:215], v[28:31]
	v_mfma_f32_16x16x32_bf16 v[20:23], v[176:179], v[220:223], v[20:23]
	v_mfma_f32_16x16x32_bf16 v[12:15], v[184:187], v[220:223], v[12:15]
	v_mfma_f32_16x16x32_bf16 v[4:7], v[176:179], v[228:231], v[4:7]
	v_mfma_f32_16x16x32_bf16 v[0:3], v[184:187], v[228:231], v[0:3]
	s_setprio 0
	s_barrier
	s_add_i32 s83, s83, 2
	s_add_u32 s64, s64, 0x100
	s_addc_u32 s65, s65, 0
	s_add_u32 s49, s49, 0x100
	s_addc_u32 s63, s63, 0
	s_cmp_gt_u32 s83, 13

; #define PG8_STAGE(bufoff, gbase, voff) do { _Pragma("unroll") for (int _i = 0; _i < 2; ++_i) \
;         __builtin_amdgcn_global_load_lds((const unsigned*)((const char*)(gbase) + (voff)[_i]), (PG8_LAS unsigned*)(lds + (bufoff) + ldsw + _i * 8192), 16, 0, 0); } while (0)
; #define PG8_LDA(dst, b, h) do { _Pragma("unroll") for (int m = 0; m < 4; ++m) _Pragma("unroll") for (int k = 0; k < 2; ++k) dst[m][k] = *(const PG8_LAS bf16x8*)(lds + PG8_SA(b, h) + aoff + m * 2048 + k * 1024); } while (0)
; #define PG8_LDB(dst, b, h) do { _Pragma("unroll") for (int n = 0; n < 2; ++n) _Pragma("unroll") for (int k = 0; k < 2; ++k) dst[n][k] = *(const PG8_LAS bf16x8*)(lds + PG8_SB(b, h) + boff + n * 2048 + k * 1024); } while (0)
; #define PG8_MMA(ai, bj, At, Bt) do { __builtin_amdgcn_s_setprio(1); _Pragma("unroll") for (int m = 0; m < 4; ++m) _Pragma("unroll") for (int n = 0; n < 2; ++n) _Pragma("unroll") for (int k = 0; k < 2; ++k) \
;         acc[ai][bj][m][n] = __builtin_amdgcn_mfma_f32_16x16x32_bf16(Bt[n][k], At[m][k], acc[ai][bj][m][n], 0, 0, 0); __builtin_amdgcn_s_setprio(0); } while (0)
; template <class Epi, class Sched, bool ALIGN_EPI = false, bool SP2 = false, bool ATILED = false>
; __device__ __forceinline__ void gemm_phase(PG8_LAS unsigned char* lds, const Gemm g, const Sched& S, const Epi& E) {
;     ...
;         const bool has_next = S.next(ui + 1, nxt);
;         const char* nA = has_next ? (const char*)g.A + (size_t)nxt.pm * tstepA : cA; const char* nB = has_next ? (const char*)g.Bt + (size_t)nxt.pn * tstep : cB;
;         for (int t = 0; t < nt; t += 2) {
;             const bool last = (t == nt - 2);
;             const char* a1 = cA + (size_t)(t + 1) * kstepA;
;             const char* a2 = last ? nA : cA + (size_t)(t + 2) * kstepA; const char* b2 = last ? nB : cB + (size_t)(t + 2) * kstep;
;             const char* a3 = a2 + kstepA; const char* b3 = b2 + kstep;
;             if (last && has_next) S.a_ready(nxt);
;             if constexpr (SP2) {
;             PG8_LDB(B0, 0, 0); PG8_LDB(B1, 0, 1); PG8_SCHED; PG8_LDA(At, 0, 0); PG8_STAGE(PG8_SA(1, 1), a1 + hstepA, voffA);
;             PG8_WAIT_V(8); PG8_WAIT_L(0); PG8_BAR; PG8_MMA(0, 0, At, B0); PG8_MMA(0, 1, At, B1); PG8_BAR; PG8_SCHED;
;             PG8_LDA(At, 0, 1); PG8_STAGE(PG8_SB(0, 0), b2, voffB); PG8_STAGE(PG8_SB(0, 1), b2 + hstep, voffB); PG8_STAGE(PG8_SA(0, 0), a2, voffA);
.LBB0_734:
	s_ashr_i32 s19, s18, 31
	s_lshl_b64 s[20:21], s[18:19], 19
	s_add_u32 s20, s44, s20
	s_addc_u32 s21, s45, s21
	s_and_b64 s[42:43], s[4:5], exec
	s_cselect_b32 s19, s21, s51
	s_cselect_b32 s49, s20, s50
	s_ashr_i32 s17, s16, 31
	s_lshl_b64 s[42:43], s[16:17], 19
	s_add_u32 s42, s46, s42
	s_addc_u32 s43, s47, s43
	s_and_b64 s[56:57], s[4:5], exec
	s_cselect_b32 s17, s43, s55
	s_cselect_b32 s70, s42, s54
	s_add_u32 s50, s50, 0x40080
	s_addc_u32 s51, s51, 0
	s_add_u32 s71, s54, 0x100
	s_addc_u32 s72, s55, 0
	s_mov_b32 s73, -2
	s_waitcnt lgkmcnt(0)
	s_waitcnt vmcnt(0)
	ds_read_b128 v[128:131], v189
	ds_read_b128 v[132:135], v189 offset:1024
	ds_read_b128 v[136:139], v189 offset:2048
	ds_read_b128 v[140:143], v189 offset:3072
	ds_read_b128 v[144:147], v190
	ds_read_b128 v[148:151], v190 offset:1024
	ds_read_b128 v[168:171], v190 offset:2048
	ds_read_b128 v[172:175], v190 offset:3072
	s_add_u32 s54, s50, 0xfffc0080
	s_addc_u32 s55, s51, -1
	s_cmp_eq_u32 s73, 12
	s_cselect_b32 s57, s19, s55
	s_cselect_b32 s56, s49, s54
	s_cselect_b32 s55, s17, s72
	s_cselect_b32 s54, s70, s71
	v_lshl_add_u64 v[184:185], s[50:51], 0, v[160:161]
	s_add_i32 m0, s58, 0xc000
	ds_read_b128 v[176:179], v191
	ds_read_b128 v[180:183], v191 offset:1024
	ds_read_b128 v[194:197], v191 offset:2048
	ds_read_b128 v[200:203], v191 offset:3072
	ds_read_b128 v[204:207], v191 offset:4096
	ds_read_b128 v[208:211], v191 offset:5120
	ds_read_b128 v[212:215], v191 offset:6144
	ds_read_b128 v[216:219], v191 offset:7168
	global_load_lds_dwordx4 v[184:185], off
	v_lshl_add_u64 v[184:185], s[50:51], 0, v[162:163]
	s_add_i32 m0, s58, 0xe000
	s_nop 0
	global_load_lds_dwordx4 v[184:185], off
	s_waitcnt vmcnt(8)
	s_waitcnt lgkmcnt(0)
	s_barrier
	s_setprio 1
	s_waitcnt lgkmcnt(0)
	v_mfma_f32_16x16x32_bf16 v[124:127], v[128:131], v[176:179], 0
	v_mfma_f32_16x16x32_bf16 v[120:123], v[136:139], v[176:179], 0
	v_mfma_f32_16x16x32_bf16 v[108:111], v[128:131], v[194:197], 0
	v_mfma_f32_16x16x32_bf16 v[104:107], v[136:139], v[194:197], 0
	v_mfma_f32_16x16x32_bf16 v[92:95], v[128:131], v[204:207], 0
	v_mfma_f32_16x16x32_bf16 v[88:91], v[136:139], v[204:207], 0
	v_mfma_f32_16x16x32_bf16 v[76:79], v[128:131], v[212:215], 0
	v_mfma_f32_16x16x32_bf16 v[72:75], v[136:139], v[212:215], 0
	v_mfma_f32_16x16x32_bf16 v[124:127], v[132:135], v[180:183], v[124:127]
	v_mfma_f32_16x16x32_bf16 v[120:123], v[140:143], v[180:183], v[120:123]
	v_mfma_f32_16x16x32_bf16 v[108:111], v[132:135], v[200:203], v[108:111]
	v_mfma_f32_16x16x32_bf16 v[104:107], v[140:143], v[200:203], v[104:107]
	v_mfma_f32_16x16x32_bf16 v[92:95], v[132:135], v[208:211], v[92:95]
	v_mfma_f32_16x16x32_bf16 v[88:91], v[140:143], v[208:211], v[88:91]
	v_mfma_f32_16x16x32_bf16 v[76:79], v[132:135], v[216:219], v[76:79]
	v_mfma_f32_16x16x32_bf16 v[72:75], v[140:143], v[216:219], v[72:75]
	s_setprio 0
	s_setprio 1
	v_mfma_f32_16x16x32_bf16 v[116:119], v[144:147], v[176:179], 0
	v_mfma_f32_16x16x32_bf16 v[112:115], v[168:171], v[176:179], 0
	v_mfma_f32_16x16x32_bf16 v[100:103], v[144:147], v[194:197], 0
	v_mfma_f32_16x16x32_bf16 v[96:99], v[168:171], v[194:197], 0
	v_mfma_f32_16x16x32_bf16 v[84:87], v[144:147], v[204:207], 0
	v_mfma_f32_16x16x32_bf16 v[80:83], v[168:171], v[204:207], 0
	v_mfma_f32_16x16x32_bf16 v[68:71], v[144:147], v[212:215], 0
	v_mfma_f32_16x16x32_bf16 v[64:67], v[168:171], v[212:215], 0
	v_mfma_f32_16x16x32_bf16 v[116:119], v[148:151], v[180:183], v[116:119]
	v_mfma_f32_16x16x32_bf16 v[112:115], v[172:175], v[180:183], v[112:115]
	v_mfma_f32_16x16x32_bf16 v[100:103], v[148:151], v[200:203], v[100:103]
	v_mfma_f32_16x16x32_bf16 v[96:99], v[172:175], v[200:203], v[96:99]
	v_mfma_f32_16x16x32_bf16 v[84:87], v[148:151], v[208:211], v[84:87]
	v_mfma_f32_16x16x32_bf16 v[80:83], v[172:175], v[208:211], v[80:83]
	v_mfma_f32_16x16x32_bf16 v[68:71], v[148:151], v[216:219], v[68:71]
	v_mfma_f32_16x16x32_bf16 v[64:67], v[172:175], v[216:219], v[64:67]
	s_setprio 0
	s_barrier
	s_add_i32 s74, s67, s29
	v_lshl_add_u64 v[184:185], s[54:55], 0, v[154:155]
	s_mov_b32 m0, s74
	ds_read_b128 v[176:179], v191 offset:16384
	ds_read_b128 v[180:183], v191 offset:17408
	ds_read_b128 v[194:197], v191 offset:18432
	ds_read_b128 v[200:203], v191 offset:19456
	ds_read_b128 v[204:207], v191 offset:20480
	ds_read_b128 v[208:211], v191 offset:21504
	ds_read_b128 v[212:215], v191 offset:22528
	ds_read_b128 v[216:219], v191 offset:23552
	global_load_lds_dwordx4 v[184:185], off
	s_add_i32 m0, s74, 0x2000
	s_add_u32 s74, s54, 0x40000
	v_lshl_add_u64 v[220:221], s[54:55], 0, v[158:159]
	s_addc_u32 s75, s55, 0
	s_add_i32 s76, s68, s29
	global_load_lds_dwordx4 v[220:221], off
	v_lshl_add_u64 v[222:223], s[74:75], 0, v[154:155]
	s_mov_b32 m0, s76
	v_lshl_add_u64 v[224:225], s[56:57], 0, v[156:157]
	global_load_lds_dwordx4 v[222:223], off
	v_lshl_add_u64 v[222:223], s[74:75], 0, v[158:159]
	s_add_i32 m0, s76, 0x2000
	s_nop 0
	global_load_lds_dwordx4 v[222:223], off
	v_lshl_add_u64 v[222:223], s[56:57], 0, v[152:153]
	s_mov_b32 m0, s58
	s_nop 0
	global_load_lds_dwordx4 v[222:223], off
	s_mov_b32 m0, s59
	s_nop 0
	global_load_lds_dwordx4 v[224:225], off
	s_waitcnt vmcnt(8)
	s_waitcnt lgkmcnt(0)
	s_barrier
; #define PG8_STAGE(bufoff, gbase, voff) do { _Pragma("unroll") for (int _i = 0; _i < 2; ++_i) \
;         __builtin_amdgcn_global_load_lds((const unsigned*)((const char*)(gbase) + (voff)[_i]), (PG8_LAS unsigned*)(lds + (bufoff) + ldsw + _i * 8192), 16, 0, 0); } while (0)
; #define PG8_LDA(dst, b, h) do { _Pragma("unroll") for (int m = 0; m < 4; ++m) _Pragma("unroll") for (int k = 0; k < 2; ++k) dst[m][k] = *(const PG8_LAS bf16x8*)(lds + PG8_SA(b, h) + aoff + m * 2048 + k * 1024); } while (0)
; #define PG8_LDB(dst, b, h) do { _Pragma("unroll") for (int n = 0; n < 2; ++n) _Pragma("unroll") for (int k = 0; k < 2; ++k) dst[n][k] = *(const PG8_LAS bf16x8*)(lds + PG8_SB(b, h) + boff + n * 2048 + k * 1024); } while (0)
; #define PG8_MMA(ai, bj, At, Bt) do { __builtin_amdgcn_s_setprio(1); _Pragma("unroll") for (int m = 0; m < 4; ++m) _Pragma("unroll") for (int n = 0; n < 2; ++n) _Pragma("unroll") for (int k = 0; k < 2; ++k) \
;         acc[ai][bj][m][n] = __builtin_amdgcn_mfma_f32_16x16x32_bf16(Bt[n][k], At[m][k], acc[ai][bj][m][n], 0, 0, 0); __builtin_amdgcn_s_setprio(0); } while (0)
; #define PG8_WAIT_V(n) asm volatile("s_waitcnt vmcnt(" #n ")" ::: "memory")
; #define PG8_WAIT_L(n) asm volatile("s_waitcnt lgkmcnt(" #n ")" ::: "memory")
; #define PG8_BAR __builtin_amdgcn_s_barrier()
; #define PG8_SCHED __builtin_amdgcn_sched_barrier(0)
; template <class Epi, class Sched, bool ALIGN_EPI = false, bool SP2 = false, bool ATILED = false>
; __device__ __forceinline__ void gemm_phase(PG8_LAS unsigned char* lds, const Gemm g, const Sched& S, const Epi& E) {
;     ...
;             PG8_WAIT_V(8); PG8_WAIT_L(0); PG8_BAR; PG8_MMA(1, 0, At, B0); PG8_MMA(1, 1, At, B1); PG8_BAR; PG8_SCHED;
;             PG8_LDB(B0, 1, 0); PG8_LDB(B1, 1, 1); PG8_SCHED; PG8_LDA(At, 1, 0); PG8_STAGE(PG8_SA(0, 1), a2 + hstepA, voffA);
;             PG8_WAIT_V(8); PG8_WAIT_L(0); PG8_BAR; PG8_MMA(0, 0, At, B0); PG8_MMA(0, 1, At, B1); PG8_BAR; PG8_SCHED;
	s_setprio 1
	s_waitcnt lgkmcnt(0)
	v_mfma_f32_16x16x32_bf16 v[60:63], v[128:131], v[176:179], 0
	v_mfma_f32_16x16x32_bf16 v[56:59], v[136:139], v[176:179], 0
	v_mfma_f32_16x16x32_bf16 v[44:47], v[128:131], v[194:197], 0
	v_mfma_f32_16x16x32_bf16 v[40:43], v[136:139], v[194:197], 0
	v_mfma_f32_16x16x32_bf16 v[28:31], v[128:131], v[204:207], 0
	v_mfma_f32_16x16x32_bf16 v[24:27], v[136:139], v[204:207], 0
	v_mfma_f32_16x16x32_bf16 v[12:15], v[128:131], v[212:215], 0
	v_mfma_f32_16x16x32_bf16 v[8:11], v[136:139], v[212:215], 0
	v_mfma_f32_16x16x32_bf16 v[60:63], v[132:135], v[180:183], v[60:63]
	v_mfma_f32_16x16x32_bf16 v[56:59], v[140:143], v[180:183], v[56:59]
	v_mfma_f32_16x16x32_bf16 v[44:47], v[132:135], v[200:203], v[44:47]
	v_mfma_f32_16x16x32_bf16 v[40:43], v[140:143], v[200:203], v[40:43]
	v_mfma_f32_16x16x32_bf16 v[28:31], v[132:135], v[208:211], v[28:31]
	v_mfma_f32_16x16x32_bf16 v[24:27], v[140:143], v[208:211], v[24:27]
	v_mfma_f32_16x16x32_bf16 v[12:15], v[132:135], v[216:219], v[12:15]
	v_mfma_f32_16x16x32_bf16 v[8:11], v[140:143], v[216:219], v[8:11]
	s_setprio 0
	s_setprio 1
	v_mfma_f32_16x16x32_bf16 v[52:55], v[144:147], v[176:179], 0
	v_mfma_f32_16x16x32_bf16 v[48:51], v[168:171], v[176:179], 0
	v_mfma_f32_16x16x32_bf16 v[36:39], v[144:147], v[194:197], 0
	v_mfma_f32_16x16x32_bf16 v[32:35], v[168:171], v[194:197], 0
	v_mfma_f32_16x16x32_bf16 v[20:23], v[144:147], v[204:207], 0
	v_mfma_f32_16x16x32_bf16 v[16:19], v[168:171], v[204:207], 0
	v_mfma_f32_16x16x32_bf16 v[4:7], v[144:147], v[212:215], 0
	v_mfma_f32_16x16x32_bf16 v[0:3], v[168:171], v[212:215], 0
	v_mfma_f32_16x16x32_bf16 v[52:55], v[148:151], v[180:183], v[52:55]
	v_mfma_f32_16x16x32_bf16 v[48:51], v[172:175], v[180:183], v[48:51]
	v_mfma_f32_16x16x32_bf16 v[36:39], v[148:151], v[200:203], v[36:39]
	v_mfma_f32_16x16x32_bf16 v[32:35], v[172:175], v[200:203], v[32:35]
	v_mfma_f32_16x16x32_bf16 v[20:23], v[148:151], v[208:211], v[20:23]
	v_mfma_f32_16x16x32_bf16 v[16:19], v[172:175], v[208:211], v[16:19]
	v_mfma_f32_16x16x32_bf16 v[4:7], v[148:151], v[216:219], v[4:7]
	v_mfma_f32_16x16x32_bf16 v[0:3], v[172:175], v[216:219], v[0:3]
	s_setprio 0
	s_barrier
	s_add_i32 s74, 0, 0x18000
	s_add_i32 s75, 0, 0x1c000
	v_add_u32_e32 v140, s74, v187
	v_add_u32_e32 v172, s75, v187
	ds_read_b128 v[128:131], v140
	ds_read_b128 v[132:135], v140 offset:1024
	ds_read_b128 v[136:139], v140 offset:2048
	ds_read_b128 v[140:143], v140 offset:3072
	ds_read_b128 v[144:147], v172
	ds_read_b128 v[148:151], v172 offset:1024
	ds_read_b128 v[168:171], v172 offset:2048
	ds_read_b128 v[172:175], v172 offset:3072
	s_add_u32 s56, s56, 0x40000
	s_addc_u32 s57, s57, 0
	s_mov_b32 m0, s60
	v_lshl_add_u64 v[226:227], s[56:57], 0, v[152:153]
	ds_read_b128 v[176:179], v191 offset:32768
	ds_read_b128 v[180:183], v191 offset:33792
	ds_read_b128 v[194:197], v191 offset:34816
	ds_read_b128 v[200:203], v191 offset:35840
	ds_read_b128 v[204:207], v191 offset:36864
	ds_read_b128 v[208:211], v191 offset:37888
	ds_read_b128 v[212:215], v191 offset:38912
	ds_read_b128 v[216:219], v191 offset:39936
	global_load_lds_dwordx4 v[226:227], off
	v_lshl_add_u64 v[226:227], s[56:57], 0, v[156:157]
	s_mov_b32 m0, s61
	s_nop 0
	global_load_lds_dwordx4 v[226:227], off
	s_waitcnt vmcnt(8)
	s_waitcnt lgkmcnt(0)
	s_barrier
	s_setprio 1
	s_waitcnt lgkmcnt(0)
	v_mfma_f32_16x16x32_bf16 v[124:127], v[128:131], v[176:179], v[124:127]
	v_mfma_f32_16x16x32_bf16 v[120:123], v[136:139], v[176:179], v[120:123]
	v_mfma_f32_16x16x32_bf16 v[108:111], v[128:131], v[194:197], v[108:111]
	v_mfma_f32_16x16x32_bf16 v[104:107], v[136:139], v[194:197], v[104:107]
	v_mfma_f32_16x16x32_bf16 v[92:95], v[128:131], v[204:207], v[92:95]
	v_mfma_f32_16x16x32_bf16 v[88:91], v[136:139], v[204:207], v[88:91]
	v_mfma_f32_16x16x32_bf16 v[76:79], v[128:131], v[212:215], v[76:79]
	v_mfma_f32_16x16x32_bf16 v[72:75], v[136:139], v[212:215], v[72:75]
	v_mfma_f32_16x16x32_bf16 v[124:127], v[132:135], v[180:183], v[124:127]
	v_mfma_f32_16x16x32_bf16 v[120:123], v[140:143], v[180:183], v[120:123]
	v_mfma_f32_16x16x32_bf16 v[108:111], v[132:135], v[200:203], v[108:111]
	v_mfma_f32_16x16x32_bf16 v[104:107], v[140:143], v[200:203], v[104:107]
	v_mfma_f32_16x16x32_bf16 v[92:95], v[132:135], v[208:211], v[92:95]
	v_mfma_f32_16x16x32_bf16 v[88:91], v[140:143], v[208:211], v[88:91]
	v_mfma_f32_16x16x32_bf16 v[76:79], v[132:135], v[216:219], v[76:79]
	v_mfma_f32_16x16x32_bf16 v[72:75], v[140:143], v[216:219], v[72:75]
	s_setprio 0
	s_setprio 1
	v_mfma_f32_16x16x32_bf16 v[116:119], v[144:147], v[176:179], v[116:119]
	v_mfma_f32_16x16x32_bf16 v[112:115], v[168:171], v[176:179], v[112:115]
	v_mfma_f32_16x16x32_bf16 v[100:103], v[144:147], v[194:197], v[100:103]
	v_mfma_f32_16x16x32_bf16 v[96:99], v[168:171], v[194:197], v[96:99]
	v_mfma_f32_16x16x32_bf16 v[84:87], v[144:147], v[204:207], v[84:87]
	v_mfma_f32_16x16x32_bf16 v[80:83], v[168:171], v[204:207], v[80:83]
	v_mfma_f32_16x16x32_bf16 v[68:71], v[144:147], v[212:215], v[68:71]
	v_mfma_f32_16x16x32_bf16 v[64:67], v[168:171], v[212:215], v[64:67]
	v_mfma_f32_16x16x32_bf16 v[116:119], v[148:151], v[180:183], v[116:119]
	v_mfma_f32_16x16x32_bf16 v[112:115], v[172:175], v[180:183], v[112:115]
	v_mfma_f32_16x16x32_bf16 v[100:103], v[148:151], v[200:203], v[100:103]
	v_mfma_f32_16x16x32_bf16 v[96:99], v[172:175], v[200:203], v[96:99]
	v_mfma_f32_16x16x32_bf16 v[84:87], v[148:151], v[208:211], v[84:87]
	v_mfma_f32_16x16x32_bf16 v[80:83], v[172:175], v[208:211], v[80:83]
	v_mfma_f32_16x16x32_bf16 v[68:71], v[148:151], v[216:219], v[68:71]
	v_mfma_f32_16x16x32_bf16 v[64:67], v[172:175], v[216:219], v[64:67]
	s_setprio 0
	s_barrier
; #define PG8_STAGE(bufoff, gbase, voff) do { _Pragma("unroll") for (int _i = 0; _i < 2; ++_i) \
;         __builtin_amdgcn_global_load_lds((const unsigned*)((const char*)(gbase) + (voff)[_i]), (PG8_LAS unsigned*)(lds + (bufoff) + ldsw + _i * 8192), 16, 0, 0); } while (0)
; #define PG8_LDA(dst, b, h) do { _Pragma("unroll") for (int m = 0; m < 4; ++m) _Pragma("unroll") for (int k = 0; k < 2; ++k) dst[m][k] = *(const PG8_LAS bf16x8*)(lds + PG8_SA(b, h) + aoff + m * 2048 + k * 1024); } while (0)
; #define PG8_MMA(ai, bj, At, Bt) do { __builtin_amdgcn_s_setprio(1); _Pragma("unroll") for (int m = 0; m < 4; ++m) _Pragma("unroll") for (int n = 0; n < 2; ++n) _Pragma("unroll") for (int k = 0; k < 2; ++k) \
;         acc[ai][bj][m][n] = __builtin_amdgcn_mfma_f32_16x16x32_bf16(Bt[n][k], At[m][k], acc[ai][bj][m][n], 0, 0, 0); __builtin_amdgcn_s_setprio(0); } while (0)
; #define PG8_WAIT_V(n) asm volatile("s_waitcnt vmcnt(" #n ")" ::: "memory")
; #define PG8_WAIT_L(n) asm volatile("s_waitcnt lgkmcnt(" #n ")" ::: "memory")
; #define PG8_BAR __builtin_amdgcn_s_barrier()
; #define PG8_SCHED __builtin_amdgcn_sched_barrier(0)
; template <class Epi, class Sched, bool ALIGN_EPI = false, bool SP2 = false, bool ATILED = false>
; __device__ __forceinline__ void gemm_phase(PG8_LAS unsigned char* lds, const Gemm g, const Sched& S, const Epi& E) {
;     ...
;         for (int t = 0; t < nt; t += 2) {
;     ...
;             PG8_LDA(At, 1, 1); PG8_STAGE(PG8_SB(1, 0), b3, voffB); PG8_STAGE(PG8_SB(1, 1), b3 + hstep, voffB); PG8_STAGE(PG8_SA(1, 0), a3, voffA);
;             PG8_WAIT_V(8); PG8_WAIT_L(0); PG8_BAR; PG8_MMA(1, 0, At, B0); PG8_MMA(1, 1, At, B1); PG8_BAR; PG8_SCHED;
	s_add_i32 s56, s74, s29
	v_lshl_add_u64 v[184:185], v[184:185], 0, s[12:13]
	s_mov_b32 m0, s56
	ds_read_b128 v[176:179], v191 offset:49152
	ds_read_b128 v[180:183], v191 offset:50176
	ds_read_b128 v[194:197], v191 offset:51200
	ds_read_b128 v[200:203], v191 offset:52224
	ds_read_b128 v[204:207], v191 offset:53248
	ds_read_b128 v[208:211], v191 offset:54272
	ds_read_b128 v[212:215], v191 offset:55296
	ds_read_b128 v[216:219], v191 offset:56320
	global_load_lds_dwordx4 v[184:185], off
	s_add_i32 m0, s56, 0x2000
	s_add_u32 s54, s54, 0x40080
	v_lshl_add_u64 v[184:185], v[220:221], 0, s[12:13]
	s_addc_u32 s55, s55, 0
	s_add_i32 s56, s75, s29
	global_load_lds_dwordx4 v[184:185], off
	v_lshl_add_u64 v[184:185], s[54:55], 0, v[154:155]
	s_mov_b32 m0, s56
	s_nop 0
	global_load_lds_dwordx4 v[184:185], off
	v_lshl_add_u64 v[184:185], s[54:55], 0, v[158:159]
	s_add_i32 m0, s56, 0x2000
	s_nop 0
	global_load_lds_dwordx4 v[184:185], off
	v_lshl_add_u64 v[184:185], v[222:223], 0, s[12:13]
	s_mov_b32 m0, s63
	s_nop 0
	global_load_lds_dwordx4 v[184:185], off
	v_lshl_add_u64 v[184:185], v[224:225], 0, s[12:13]
	s_mov_b32 m0, s64
	s_nop 0
	global_load_lds_dwordx4 v[184:185], off
	s_waitcnt vmcnt(8)
	s_waitcnt lgkmcnt(0)
	s_barrier
	s_setprio 1
	s_waitcnt lgkmcnt(0)
	v_mfma_f32_16x16x32_bf16 v[60:63], v[128:131], v[176:179], v[60:63]
	v_mfma_f32_16x16x32_bf16 v[56:59], v[136:139], v[176:179], v[56:59]
	v_mfma_f32_16x16x32_bf16 v[44:47], v[128:131], v[194:197], v[44:47]
	v_mfma_f32_16x16x32_bf16 v[40:43], v[136:139], v[194:197], v[40:43]
	v_mfma_f32_16x16x32_bf16 v[28:31], v[128:131], v[204:207], v[28:31]
	v_mfma_f32_16x16x32_bf16 v[24:27], v[136:139], v[204:207], v[24:27]
	v_mfma_f32_16x16x32_bf16 v[12:15], v[128:131], v[212:215], v[12:15]
	v_mfma_f32_16x16x32_bf16 v[8:11], v[136:139], v[212:215], v[8:11]
	v_mfma_f32_16x16x32_bf16 v[60:63], v[132:135], v[180:183], v[60:63]
	v_mfma_f32_16x16x32_bf16 v[56:59], v[140:143], v[180:183], v[56:59]
	v_mfma_f32_16x16x32_bf16 v[44:47], v[132:135], v[200:203], v[44:47]
	v_mfma_f32_16x16x32_bf16 v[40:43], v[140:143], v[200:203], v[40:43]
	v_mfma_f32_16x16x32_bf16 v[28:31], v[132:135], v[208:211], v[28:31]
	v_mfma_f32_16x16x32_bf16 v[24:27], v[140:143], v[208:211], v[24:27]
	v_mfma_f32_16x16x32_bf16 v[12:15], v[132:135], v[216:219], v[12:15]
	v_mfma_f32_16x16x32_bf16 v[8:11], v[140:143], v[216:219], v[8:11]
	s_setprio 0
	s_setprio 1
	v_mfma_f32_16x16x32_bf16 v[52:55], v[144:147], v[176:179], v[52:55]
	v_mfma_f32_16x16x32_bf16 v[48:51], v[168:171], v[176:179], v[48:51]
	v_mfma_f32_16x16x32_bf16 v[36:39], v[144:147], v[194:197], v[36:39]
	v_mfma_f32_16x16x32_bf16 v[32:35], v[168:171], v[194:197], v[32:35]
	v_mfma_f32_16x16x32_bf16 v[20:23], v[144:147], v[204:207], v[20:23]
	v_mfma_f32_16x16x32_bf16 v[16:19], v[168:171], v[204:207], v[16:19]
	v_mfma_f32_16x16x32_bf16 v[4:7], v[144:147], v[212:215], v[4:7]
	v_mfma_f32_16x16x32_bf16 v[0:3], v[168:171], v[212:215], v[0:3]
	v_mfma_f32_16x16x32_bf16 v[52:55], v[148:151], v[180:183], v[52:55]
	v_mfma_f32_16x16x32_bf16 v[48:51], v[172:175], v[180:183], v[48:51]
	v_mfma_f32_16x16x32_bf16 v[36:39], v[148:151], v[200:203], v[36:39]
	v_mfma_f32_16x16x32_bf16 v[32:35], v[172:175], v[200:203], v[32:35]
	v_mfma_f32_16x16x32_bf16 v[20:23], v[148:151], v[208:211], v[20:23]
	v_mfma_f32_16x16x32_bf16 v[16:19], v[172:175], v[208:211], v[16:19]
	v_mfma_f32_16x16x32_bf16 v[4:7], v[148:151], v[216:219], v[4:7]
	v_mfma_f32_16x16x32_bf16 v[0:3], v[172:175], v[216:219], v[0:3]
	s_setprio 0
	s_barrier
	s_add_i32 s73, s73, 2
	s_add_u32 s50, s50, 0x100
	s_addc_u32 s51, s51, 0
	s_add_u32 s71, s71, 0x100
	s_addc_u32 s72, s72, 0
	s_cmp_gt_u32 s73, 13

; #define PG8_STAGE(bufoff, gbase, voff) do { _Pragma("unroll") for (int _i = 0; _i < 2; ++_i) \
;         __builtin_amdgcn_global_load_lds((const unsigned*)((const char*)(gbase) + (voff)[_i]), (PG8_LAS unsigned*)(lds + (bufoff) + ldsw + _i * 8192), 16, 0, 0); } while (0)
; #define PG8_LDA(dst, b, h) do { _Pragma("unroll") for (int m = 0; m < 4; ++m) _Pragma("unroll") for (int k = 0; k < 2; ++k) dst[m][k] = *(const PG8_LAS bf16x8*)(lds + PG8_SA(b, h) + aoff + m * 2048 + k * 1024); } while (0)
; #define PG8_LDB(dst, b, h) do { _Pragma("unroll") for (int n = 0; n < 2; ++n) _Pragma("unroll") for (int k = 0; k < 2; ++k) dst[n][k] = *(const PG8_LAS bf16x8*)(lds + PG8_SB(b, h) + boff + n * 2048 + k * 1024); } while (0)
; #define PG8_MMA(ai, bj, At, Bt) do { __builtin_amdgcn_s_setprio(1); _Pragma("unroll") for (int m = 0; m < 4; ++m) _Pragma("unroll") for (int n = 0; n < 2; ++n) _Pragma("unroll") for (int k = 0; k < 2; ++k) \
;         acc[ai][bj][m][n] = __builtin_amdgcn_mfma_f32_16x16x32_bf16(Bt[n][k], At[m][k], acc[ai][bj][m][n], 0, 0, 0); __builtin_amdgcn_s_setprio(0); } while (0)
; template <class Epi, class Sched, bool ALIGN_EPI = false, bool SP2 = false, bool ATILED = false>
; __device__ __forceinline__ void gemm_phase(PG8_LAS unsigned char* lds, const Gemm g, const Sched& S, const Epi& E) {
;     ...
;         const bool has_next = S.next(ui + 1, nxt);
;         const char* nA = has_next ? (const char*)g.A + (size_t)nxt.pm * tstepA : cA; const char* nB = has_next ? (const char*)g.Bt + (size_t)nxt.pn * tstep : cB;
;         for (int t = 0; t < nt; t += 2) {
;             const bool last = (t == nt - 2);
;             const char* a1 = cA + (size_t)(t + 1) * kstepA;
;             const char* a2 = last ? nA : cA + (size_t)(t + 2) * kstepA; const char* b2 = last ? nB : cB + (size_t)(t + 2) * kstep;
;             const char* a3 = a2 + kstepA; const char* b3 = b2 + kstep;
;             if (last && has_next) S.a_ready(nxt);
;             if constexpr (SP2) {
;             PG8_LDB(B0, 0, 0); PG8_LDB(B1, 0, 1); PG8_SCHED; PG8_LDA(At, 0, 0); PG8_STAGE(PG8_SA(1, 1), a1 + hstepA, voffA);
;             PG8_WAIT_V(8); PG8_WAIT_L(0); PG8_BAR; PG8_MMA(0, 0, At, B0); PG8_MMA(0, 1, At, B1); PG8_BAR; PG8_SCHED;
;             PG8_LDA(At, 0, 1); PG8_STAGE(PG8_SB(0, 0), b2, voffB); PG8_STAGE(PG8_SB(0, 1), b2 + hstep, voffB); PG8_STAGE(PG8_SA(0, 0), a2, voffA);
.LBB0_816:
	s_ashr_i32 s13, s12, 31
	s_lshl_b64 s[14:15], s[12:13], 19
	s_add_u32 s14, s26, s14
	s_addc_u32 s15, s27, s15
	s_and_b64 s[16:17], s[0:1], exec
	s_cselect_b32 s13, s15, s21
	s_cselect_b32 s64, s14, s20
	s_ashr_i32 s11, s10, 31
	s_lshl_b64 s[16:17], s[10:11], 19
	s_add_u32 s16, s40, s16
	s_addc_u32 s17, s41, s17
	s_and_b64 s[44:45], s[0:1], exec
	s_cselect_b32 s11, s17, s43
	s_cselect_b32 s65, s16, s42
	s_add_u32 s20, s20, 0x40080
	s_addc_u32 s21, s21, 0
	s_add_u32 s66, s42, 0x100
	s_addc_u32 s67, s43, 0
	s_mov_b32 s68, -2
	s_waitcnt vmcnt(0)
	ds_read_b128 v[150:153], v156
	ds_read_b128 v[162:165], v156 offset:1024
	ds_read_b128 v[166:169], v156 offset:2048
	ds_read_b128 v[170:173], v156 offset:3072
	ds_read_b128 v[174:177], v157
	ds_read_b128 v[178:181], v157 offset:1024
	ds_read_b128 v[182:185], v157 offset:2048
	ds_read_b128 v[186:189], v157 offset:3072
	s_add_u32 s42, s20, 0xfffc0080
	s_addc_u32 s43, s21, -1
	s_cmp_eq_u32 s68, 12
	s_cselect_b32 s45, s13, s43
	s_cselect_b32 s44, s64, s42
	s_cselect_b32 s43, s11, s67
	s_cselect_b32 s42, s65, s66
	v_lshl_add_u64 v[224:225], s[20:21], 0, v[140:141]
	s_add_i32 m0, s19, 0xc000
	ds_read_b128 v[190:193], v158
	ds_read_b128 v[194:197], v158 offset:1024
	ds_read_b128 v[200:203], v158 offset:2048
	ds_read_b128 v[204:207], v158 offset:3072
	ds_read_b128 v[208:211], v158 offset:4096
	ds_read_b128 v[212:215], v158 offset:5120
	ds_read_b128 v[216:219], v158 offset:6144
	ds_read_b128 v[220:223], v158 offset:7168
	global_load_lds_dwordx4 v[224:225], off
	v_lshl_add_u64 v[224:225], s[20:21], 0, v[142:143]
	s_add_i32 m0, s19, 0xe000
	s_nop 0
	global_load_lds_dwordx4 v[224:225], off
	s_waitcnt vmcnt(8)
	s_waitcnt lgkmcnt(0)
	s_barrier
	s_setprio 1
	s_waitcnt lgkmcnt(0)
	v_mfma_f32_16x16x32_bf16 v[124:127], v[150:153], v[190:193], 0
	v_mfma_f32_16x16x32_bf16 v[120:123], v[166:169], v[190:193], 0
	v_mfma_f32_16x16x32_bf16 v[108:111], v[150:153], v[200:203], 0
	v_mfma_f32_16x16x32_bf16 v[104:107], v[166:169], v[200:203], 0
	v_mfma_f32_16x16x32_bf16 v[92:95], v[150:153], v[208:211], 0
	v_mfma_f32_16x16x32_bf16 v[88:91], v[166:169], v[208:211], 0
	v_mfma_f32_16x16x32_bf16 v[76:79], v[150:153], v[216:219], 0
	v_mfma_f32_16x16x32_bf16 v[72:75], v[166:169], v[216:219], 0
	v_mfma_f32_16x16x32_bf16 v[124:127], v[162:165], v[194:197], v[124:127]
	v_mfma_f32_16x16x32_bf16 v[120:123], v[170:173], v[194:197], v[120:123]
	v_mfma_f32_16x16x32_bf16 v[108:111], v[162:165], v[204:207], v[108:111]
	v_mfma_f32_16x16x32_bf16 v[104:107], v[170:173], v[204:207], v[104:107]
	v_mfma_f32_16x16x32_bf16 v[92:95], v[162:165], v[212:215], v[92:95]
	v_mfma_f32_16x16x32_bf16 v[88:91], v[170:173], v[212:215], v[88:91]
	v_mfma_f32_16x16x32_bf16 v[76:79], v[162:165], v[220:223], v[76:79]
	v_mfma_f32_16x16x32_bf16 v[72:75], v[170:173], v[220:223], v[72:75]
	s_setprio 0
	s_setprio 1
	v_mfma_f32_16x16x32_bf16 v[116:119], v[174:177], v[190:193], 0
	v_mfma_f32_16x16x32_bf16 v[112:115], v[182:185], v[190:193], 0
	v_mfma_f32_16x16x32_bf16 v[100:103], v[174:177], v[200:203], 0
	v_mfma_f32_16x16x32_bf16 v[96:99], v[182:185], v[200:203], 0
	v_mfma_f32_16x16x32_bf16 v[84:87], v[174:177], v[208:211], 0
	v_mfma_f32_16x16x32_bf16 v[80:83], v[182:185], v[208:211], 0
	v_mfma_f32_16x16x32_bf16 v[68:71], v[174:177], v[216:219], 0
	v_mfma_f32_16x16x32_bf16 v[64:67], v[182:185], v[216:219], 0
	v_mfma_f32_16x16x32_bf16 v[116:119], v[178:181], v[194:197], v[116:119]
	v_mfma_f32_16x16x32_bf16 v[112:115], v[186:189], v[194:197], v[112:115]
	v_mfma_f32_16x16x32_bf16 v[100:103], v[178:181], v[204:207], v[100:103]
	v_mfma_f32_16x16x32_bf16 v[96:99], v[186:189], v[204:207], v[96:99]
	v_mfma_f32_16x16x32_bf16 v[84:87], v[178:181], v[212:215], v[84:87]
	v_mfma_f32_16x16x32_bf16 v[80:83], v[186:189], v[212:215], v[80:83]
	v_mfma_f32_16x16x32_bf16 v[68:71], v[178:181], v[220:223], v[68:71]
	v_mfma_f32_16x16x32_bf16 v[64:67], v[186:189], v[220:223], v[64:67]
	s_setprio 0
	s_barrier
	s_add_i32 s69, s60, s46
	v_lshl_add_u64 v[224:225], s[42:43], 0, v[130:131]
	s_mov_b32 m0, s69
	ds_read_b128 v[190:193], v158 offset:16384
	ds_read_b128 v[194:197], v158 offset:17408
	ds_read_b128 v[200:203], v158 offset:18432
	ds_read_b128 v[204:207], v158 offset:19456
	ds_read_b128 v[208:211], v158 offset:20480
	ds_read_b128 v[212:215], v158 offset:21504
	ds_read_b128 v[216:219], v158 offset:22528
	ds_read_b128 v[220:223], v158 offset:23552
	global_load_lds_dwordx4 v[224:225], off
	s_add_i32 m0, s69, 0x2000
	s_add_u32 s70, s42, 0x40000
	v_lshl_add_u64 v[226:227], s[42:43], 0, v[134:135]
	s_addc_u32 s71, s43, 0
	s_add_i32 s69, s61, s46
	global_load_lds_dwordx4 v[226:227], off
	v_lshl_add_u64 v[228:229], s[70:71], 0, v[130:131]
	s_mov_b32 m0, s69
	v_lshl_add_u64 v[230:231], s[44:45], 0, v[132:133]
	global_load_lds_dwordx4 v[228:229], off
	v_lshl_add_u64 v[228:229], s[70:71], 0, v[134:135]
	s_add_i32 m0, s69, 0x2000
	s_nop 0
	global_load_lds_dwordx4 v[228:229], off
	v_lshl_add_u64 v[228:229], s[44:45], 0, v[128:129]
	s_mov_b32 m0, s19
	s_nop 0
	global_load_lds_dwordx4 v[228:229], off
	s_mov_b32 m0, s48
	s_nop 0
	global_load_lds_dwordx4 v[230:231], off
	s_waitcnt vmcnt(8)
	s_waitcnt lgkmcnt(0)
	s_barrier
; #define PG8_STAGE(bufoff, gbase, voff) do { _Pragma("unroll") for (int _i = 0; _i < 2; ++_i) \
;         __builtin_amdgcn_global_load_lds((const unsigned*)((const char*)(gbase) + (voff)[_i]), (PG8_LAS unsigned*)(lds + (bufoff) + ldsw + _i * 8192), 16, 0, 0); } while (0)
; #define PG8_LDA(dst, b, h) do { _Pragma("unroll") for (int m = 0; m < 4; ++m) _Pragma("unroll") for (int k = 0; k < 2; ++k) dst[m][k] = *(const PG8_LAS bf16x8*)(lds + PG8_SA(b, h) + aoff + m * 2048 + k * 1024); } while (0)
; #define PG8_LDB(dst, b, h) do { _Pragma("unroll") for (int n = 0; n < 2; ++n) _Pragma("unroll") for (int k = 0; k < 2; ++k) dst[n][k] = *(const PG8_LAS bf16x8*)(lds + PG8_SB(b, h) + boff + n * 2048 + k * 1024); } while (0)
; #define PG8_MMA(ai, bj, At, Bt) do { __builtin_amdgcn_s_setprio(1); _Pragma("unroll") for (int m = 0; m < 4; ++m) _Pragma("unroll") for (int n = 0; n < 2; ++n) _Pragma("unroll") for (int k = 0; k < 2; ++k) \
;         acc[ai][bj][m][n] = __builtin_amdgcn_mfma_f32_16x16x32_bf16(Bt[n][k], At[m][k], acc[ai][bj][m][n], 0, 0, 0); __builtin_amdgcn_s_setprio(0); } while (0)
; #define PG8_WAIT_V(n) asm volatile("s_waitcnt vmcnt(" #n ")" ::: "memory")
; #define PG8_WAIT_L(n) asm volatile("s_waitcnt lgkmcnt(" #n ")" ::: "memory")
; #define PG8_BAR __builtin_amdgcn_s_barrier()
; #define PG8_SCHED __builtin_amdgcn_sched_barrier(0)
; template <class Epi, class Sched, bool ALIGN_EPI = false, bool SP2 = false, bool ATILED = false>
; __device__ __forceinline__ void gemm_phase(PG8_LAS unsigned char* lds, const Gemm g, const Sched& S, const Epi& E) {
;     ...
;             PG8_WAIT_V(8); PG8_WAIT_L(0); PG8_BAR; PG8_MMA(1, 0, At, B0); PG8_MMA(1, 1, At, B1); PG8_BAR; PG8_SCHED;
;             PG8_LDB(B0, 1, 0); PG8_LDB(B1, 1, 1); PG8_SCHED; PG8_LDA(At, 1, 0); PG8_STAGE(PG8_SA(0, 1), a2 + hstepA, voffA);
;             PG8_WAIT_V(8); PG8_WAIT_L(0); PG8_BAR; PG8_MMA(0, 0, At, B0); PG8_MMA(0, 1, At, B1); PG8_BAR; PG8_SCHED;
	s_setprio 1
	s_waitcnt lgkmcnt(0)
	v_mfma_f32_16x16x32_bf16 v[60:63], v[150:153], v[190:193], 0
	v_mfma_f32_16x16x32_bf16 v[56:59], v[166:169], v[190:193], 0
	v_mfma_f32_16x16x32_bf16 v[44:47], v[150:153], v[200:203], 0
	v_mfma_f32_16x16x32_bf16 v[40:43], v[166:169], v[200:203], 0
	v_mfma_f32_16x16x32_bf16 v[28:31], v[150:153], v[208:211], 0
	v_mfma_f32_16x16x32_bf16 v[24:27], v[166:169], v[208:211], 0
	v_mfma_f32_16x16x32_bf16 v[12:15], v[150:153], v[216:219], 0
	v_mfma_f32_16x16x32_bf16 v[8:11], v[166:169], v[216:219], 0
	v_mfma_f32_16x16x32_bf16 v[60:63], v[162:165], v[194:197], v[60:63]
	v_mfma_f32_16x16x32_bf16 v[56:59], v[170:173], v[194:197], v[56:59]
	v_mfma_f32_16x16x32_bf16 v[44:47], v[162:165], v[204:207], v[44:47]
	v_mfma_f32_16x16x32_bf16 v[40:43], v[170:173], v[204:207], v[40:43]
	v_mfma_f32_16x16x32_bf16 v[28:31], v[162:165], v[212:215], v[28:31]
	v_mfma_f32_16x16x32_bf16 v[24:27], v[170:173], v[212:215], v[24:27]
	v_mfma_f32_16x16x32_bf16 v[12:15], v[162:165], v[220:223], v[12:15]
	v_mfma_f32_16x16x32_bf16 v[8:11], v[170:173], v[220:223], v[8:11]
	s_setprio 0
	s_setprio 1
	v_mfma_f32_16x16x32_bf16 v[52:55], v[174:177], v[190:193], 0
	v_mfma_f32_16x16x32_bf16 v[48:51], v[182:185], v[190:193], 0
	v_mfma_f32_16x16x32_bf16 v[36:39], v[174:177], v[200:203], 0
	v_mfma_f32_16x16x32_bf16 v[32:35], v[182:185], v[200:203], 0
	v_mfma_f32_16x16x32_bf16 v[20:23], v[174:177], v[208:211], 0
	v_mfma_f32_16x16x32_bf16 v[16:19], v[182:185], v[208:211], 0
	v_mfma_f32_16x16x32_bf16 v[4:7], v[174:177], v[216:219], 0
	v_mfma_f32_16x16x32_bf16 v[0:3], v[182:185], v[216:219], 0
	v_mfma_f32_16x16x32_bf16 v[52:55], v[178:181], v[194:197], v[52:55]
	v_mfma_f32_16x16x32_bf16 v[48:51], v[186:189], v[194:197], v[48:51]
	v_mfma_f32_16x16x32_bf16 v[36:39], v[178:181], v[204:207], v[36:39]
	v_mfma_f32_16x16x32_bf16 v[32:35], v[186:189], v[204:207], v[32:35]
	v_mfma_f32_16x16x32_bf16 v[20:23], v[178:181], v[212:215], v[20:23]
	v_mfma_f32_16x16x32_bf16 v[16:19], v[186:189], v[212:215], v[16:19]
	v_mfma_f32_16x16x32_bf16 v[4:7], v[178:181], v[220:223], v[4:7]
	v_mfma_f32_16x16x32_bf16 v[0:3], v[186:189], v[220:223], v[0:3]
	s_setprio 0
	s_barrier
	s_add_i32 s69, 0, 0x18000
	v_add_u32_e32 v136, s69, v155
	s_add_i32 s70, 0, 0x1c000
	ds_read_b128 v[150:153], v136
	ds_read_b128 v[162:165], v136 offset:1024
	ds_read_b128 v[166:169], v136 offset:2048
	ds_read_b128 v[170:173], v136 offset:3072
	v_add_u32_e32 v136, s70, v155
	ds_read_b128 v[174:177], v136
	ds_read_b128 v[178:181], v136 offset:1024
	ds_read_b128 v[182:185], v136 offset:2048
	ds_read_b128 v[186:189], v136 offset:3072
	s_add_u32 s44, s44, 0x40000
	s_addc_u32 s45, s45, 0
	s_mov_b32 m0, s49
	v_lshl_add_u64 v[232:233], s[44:45], 0, v[128:129]
	ds_read_b128 v[190:193], v158 offset:32768
	ds_read_b128 v[194:197], v158 offset:33792
	ds_read_b128 v[200:203], v158 offset:34816
	ds_read_b128 v[204:207], v158 offset:35840
	ds_read_b128 v[208:211], v158 offset:36864
	ds_read_b128 v[212:215], v158 offset:37888
	ds_read_b128 v[216:219], v158 offset:38912
	ds_read_b128 v[220:223], v158 offset:39936
	global_load_lds_dwordx4 v[232:233], off
	v_lshl_add_u64 v[232:233], s[44:45], 0, v[132:133]
	s_mov_b32 m0, s50
	s_nop 0
	global_load_lds_dwordx4 v[232:233], off
	s_waitcnt vmcnt(8)
	s_waitcnt lgkmcnt(0)
	s_barrier
	s_setprio 1
	s_waitcnt lgkmcnt(0)
	v_mfma_f32_16x16x32_bf16 v[124:127], v[150:153], v[190:193], v[124:127]
	v_mfma_f32_16x16x32_bf16 v[120:123], v[166:169], v[190:193], v[120:123]
	v_mfma_f32_16x16x32_bf16 v[108:111], v[150:153], v[200:203], v[108:111]
	v_mfma_f32_16x16x32_bf16 v[104:107], v[166:169], v[200:203], v[104:107]
	v_mfma_f32_16x16x32_bf16 v[92:95], v[150:153], v[208:211], v[92:95]
	v_mfma_f32_16x16x32_bf16 v[88:91], v[166:169], v[208:211], v[88:91]
	v_mfma_f32_16x16x32_bf16 v[76:79], v[150:153], v[216:219], v[76:79]
	v_mfma_f32_16x16x32_bf16 v[72:75], v[166:169], v[216:219], v[72:75]
	v_mfma_f32_16x16x32_bf16 v[124:127], v[162:165], v[194:197], v[124:127]
	v_mfma_f32_16x16x32_bf16 v[120:123], v[170:173], v[194:197], v[120:123]
	v_mfma_f32_16x16x32_bf16 v[108:111], v[162:165], v[204:207], v[108:111]
	v_mfma_f32_16x16x32_bf16 v[104:107], v[170:173], v[204:207], v[104:107]
	v_mfma_f32_16x16x32_bf16 v[92:95], v[162:165], v[212:215], v[92:95]
	v_mfma_f32_16x16x32_bf16 v[88:91], v[170:173], v[212:215], v[88:91]
	v_mfma_f32_16x16x32_bf16 v[76:79], v[162:165], v[220:223], v[76:79]
	v_mfma_f32_16x16x32_bf16 v[72:75], v[170:173], v[220:223], v[72:75]
	s_setprio 0
	s_setprio 1
	v_mfma_f32_16x16x32_bf16 v[116:119], v[174:177], v[190:193], v[116:119]
	v_mfma_f32_16x16x32_bf16 v[112:115], v[182:185], v[190:193], v[112:115]
	v_mfma_f32_16x16x32_bf16 v[100:103], v[174:177], v[200:203], v[100:103]
	v_mfma_f32_16x16x32_bf16 v[96:99], v[182:185], v[200:203], v[96:99]
	v_mfma_f32_16x16x32_bf16 v[84:87], v[174:177], v[208:211], v[84:87]
	v_mfma_f32_16x16x32_bf16 v[80:83], v[182:185], v[208:211], v[80:83]
	v_mfma_f32_16x16x32_bf16 v[68:71], v[174:177], v[216:219], v[68:71]
	v_mfma_f32_16x16x32_bf16 v[64:67], v[182:185], v[216:219], v[64:67]
	v_mfma_f32_16x16x32_bf16 v[116:119], v[178:181], v[194:197], v[116:119]
	v_mfma_f32_16x16x32_bf16 v[112:115], v[186:189], v[194:197], v[112:115]
	v_mfma_f32_16x16x32_bf16 v[100:103], v[178:181], v[204:207], v[100:103]
	v_mfma_f32_16x16x32_bf16 v[96:99], v[186:189], v[204:207], v[96:99]
	v_mfma_f32_16x16x32_bf16 v[84:87], v[178:181], v[212:215], v[84:87]
	v_mfma_f32_16x16x32_bf16 v[80:83], v[186:189], v[212:215], v[80:83]
	v_mfma_f32_16x16x32_bf16 v[68:71], v[178:181], v[220:223], v[68:71]
	v_mfma_f32_16x16x32_bf16 v[64:67], v[186:189], v[220:223], v[64:67]
	s_setprio 0
	s_barrier
; #define PG8_STAGE(bufoff, gbase, voff) do { _Pragma("unroll") for (int _i = 0; _i < 2; ++_i) \
;         __builtin_amdgcn_global_load_lds((const unsigned*)((const char*)(gbase) + (voff)[_i]), (PG8_LAS unsigned*)(lds + (bufoff) + ldsw + _i * 8192), 16, 0, 0); } while (0)
; #define PG8_LDA(dst, b, h) do { _Pragma("unroll") for (int m = 0; m < 4; ++m) _Pragma("unroll") for (int k = 0; k < 2; ++k) dst[m][k] = *(const PG8_LAS bf16x8*)(lds + PG8_SA(b, h) + aoff + m * 2048 + k * 1024); } while (0)
; #define PG8_MMA(ai, bj, At, Bt) do { __builtin_amdgcn_s_setprio(1); _Pragma("unroll") for (int m = 0; m < 4; ++m) _Pragma("unroll") for (int n = 0; n < 2; ++n) _Pragma("unroll") for (int k = 0; k < 2; ++k) \
;         acc[ai][bj][m][n] = __builtin_amdgcn_mfma_f32_16x16x32_bf16(Bt[n][k], At[m][k], acc[ai][bj][m][n], 0, 0, 0); __builtin_amdgcn_s_setprio(0); } while (0)
; #define PG8_WAIT_V(n) asm volatile("s_waitcnt vmcnt(" #n ")" ::: "memory")
; #define PG8_WAIT_L(n) asm volatile("s_waitcnt lgkmcnt(" #n ")" ::: "memory")
; #define PG8_BAR __builtin_amdgcn_s_barrier()
; #define PG8_SCHED __builtin_amdgcn_sched_barrier(0)
; template <class Epi, class Sched, bool ALIGN_EPI = false, bool SP2 = false, bool ATILED = false>
; __device__ __forceinline__ void gemm_phase(PG8_LAS unsigned char* lds, const Gemm g, const Sched& S, const Epi& E) {
;     ...
;         for (int t = 0; t < nt; t += 2) {
;     ...
;             PG8_LDA(At, 1, 1); PG8_STAGE(PG8_SB(1, 0), b3, voffB); PG8_STAGE(PG8_SB(1, 1), b3 + hstep, voffB); PG8_STAGE(PG8_SA(1, 0), a3, voffA);
;             PG8_WAIT_V(8); PG8_WAIT_L(0); PG8_BAR; PG8_MMA(1, 0, At, B0); PG8_MMA(1, 1, At, B1); PG8_BAR; PG8_SCHED;
	s_add_i32 s44, s69, s46
	v_lshl_add_u64 v[224:225], v[224:225], 0, s[6:7]
	s_mov_b32 m0, s44
	ds_read_b128 v[190:193], v158 offset:49152
	ds_read_b128 v[194:197], v158 offset:50176
	ds_read_b128 v[200:203], v158 offset:51200
	ds_read_b128 v[204:207], v158 offset:52224
	ds_read_b128 v[208:211], v158 offset:53248
	ds_read_b128 v[212:215], v158 offset:54272
	ds_read_b128 v[216:219], v158 offset:55296
	ds_read_b128 v[220:223], v158 offset:56320
	global_load_lds_dwordx4 v[224:225], off
	s_add_i32 m0, s44, 0x2000
	s_add_u32 s42, s42, 0x40080
	v_lshl_add_u64 v[224:225], v[226:227], 0, s[6:7]
	s_addc_u32 s43, s43, 0
	s_add_i32 s44, s70, s46
	global_load_lds_dwordx4 v[224:225], off
	v_lshl_add_u64 v[224:225], s[42:43], 0, v[130:131]
	s_mov_b32 m0, s44
	s_nop 0
	global_load_lds_dwordx4 v[224:225], off
	v_lshl_add_u64 v[224:225], s[42:43], 0, v[134:135]
	s_add_i32 m0, s44, 0x2000
	s_nop 0
	global_load_lds_dwordx4 v[224:225], off
	v_lshl_add_u64 v[224:225], v[228:229], 0, s[6:7]
	s_mov_b32 m0, s58
	s_nop 0
	global_load_lds_dwordx4 v[224:225], off
	v_lshl_add_u64 v[224:225], v[230:231], 0, s[6:7]
	s_mov_b32 m0, s59
	s_nop 0
	global_load_lds_dwordx4 v[224:225], off
	s_waitcnt vmcnt(8)
	s_waitcnt lgkmcnt(0)
	s_barrier
	s_setprio 1
	s_waitcnt lgkmcnt(0)
	v_mfma_f32_16x16x32_bf16 v[60:63], v[150:153], v[190:193], v[60:63]
	v_mfma_f32_16x16x32_bf16 v[56:59], v[166:169], v[190:193], v[56:59]
	v_mfma_f32_16x16x32_bf16 v[44:47], v[150:153], v[200:203], v[44:47]
	v_mfma_f32_16x16x32_bf16 v[40:43], v[166:169], v[200:203], v[40:43]
	v_mfma_f32_16x16x32_bf16 v[28:31], v[150:153], v[208:211], v[28:31]
	v_mfma_f32_16x16x32_bf16 v[24:27], v[166:169], v[208:211], v[24:27]
	v_mfma_f32_16x16x32_bf16 v[12:15], v[150:153], v[216:219], v[12:15]
	v_mfma_f32_16x16x32_bf16 v[8:11], v[166:169], v[216:219], v[8:11]
	v_mfma_f32_16x16x32_bf16 v[60:63], v[162:165], v[194:197], v[60:63]
	v_mfma_f32_16x16x32_bf16 v[56:59], v[170:173], v[194:197], v[56:59]
	v_mfma_f32_16x16x32_bf16 v[44:47], v[162:165], v[204:207], v[44:47]
	v_mfma_f32_16x16x32_bf16 v[40:43], v[170:173], v[204:207], v[40:43]
	v_mfma_f32_16x16x32_bf16 v[28:31], v[162:165], v[212:215], v[28:31]
	v_mfma_f32_16x16x32_bf16 v[24:27], v[170:173], v[212:215], v[24:27]
	v_mfma_f32_16x16x32_bf16 v[12:15], v[162:165], v[220:223], v[12:15]
	v_mfma_f32_16x16x32_bf16 v[8:11], v[170:173], v[220:223], v[8:11]
	s_setprio 0
	s_setprio 1
	v_mfma_f32_16x16x32_bf16 v[52:55], v[174:177], v[190:193], v[52:55]
	v_mfma_f32_16x16x32_bf16 v[48:51], v[182:185], v[190:193], v[48:51]
	v_mfma_f32_16x16x32_bf16 v[36:39], v[174:177], v[200:203], v[36:39]
	v_mfma_f32_16x16x32_bf16 v[32:35], v[182:185], v[200:203], v[32:35]
	v_mfma_f32_16x16x32_bf16 v[20:23], v[174:177], v[208:211], v[20:23]
	v_mfma_f32_16x16x32_bf16 v[16:19], v[182:185], v[208:211], v[16:19]
	v_mfma_f32_16x16x32_bf16 v[4:7], v[174:177], v[216:219], v[4:7]
	v_mfma_f32_16x16x32_bf16 v[0:3], v[182:185], v[216:219], v[0:3]
	v_mfma_f32_16x16x32_bf16 v[52:55], v[178:181], v[194:197], v[52:55]
	v_mfma_f32_16x16x32_bf16 v[48:51], v[186:189], v[194:197], v[48:51]
	v_mfma_f32_16x16x32_bf16 v[36:39], v[178:181], v[204:207], v[36:39]
	v_mfma_f32_16x16x32_bf16 v[32:35], v[186:189], v[204:207], v[32:35]
	v_mfma_f32_16x16x32_bf16 v[20:23], v[178:181], v[212:215], v[20:23]
	v_mfma_f32_16x16x32_bf16 v[16:19], v[186:189], v[212:215], v[16:19]
	v_mfma_f32_16x16x32_bf16 v[4:7], v[178:181], v[220:223], v[4:7]
	v_mfma_f32_16x16x32_bf16 v[0:3], v[186:189], v[220:223], v[0:3]
	s_setprio 0
	s_barrier
	s_add_i32 s68, s68, 2
	s_add_u32 s20, s20, 0x100
	s_addc_u32 s21, s21, 0
	s_add_u32 s66, s66, 0x100
	s_addc_u32 s67, s67, 0
	s_cmp_gt_u32 s68, 13
